# GEMM k-loops (outproj, merge x2, inproj x2): global loads and ds_writes interleaved between MFMAs, double-buffered LDS fragment reads
# speedup vs baseline: 1.1831x; 1.0415x over previous
; #define G_STORE(ST, S, unused) do { char* d_ = smem + (ST) * STAGE; \
;     *(uint4*)(d_ + alo[0]) = S##a0; *(uint4*)(d_ + alo[1]) = S##a1; *(uint4*)(d_ + alo[2]) = S##a2; *(uint4*)(d_ + alo[3]) = S##a3; \
;     *(uint4*)(d_ + blo[0]) = S##b0; *(uint4*)(d_ + blo[1]) = S##b1; \
;     if (NBCH == 4) { *(uint4*)(d_ + blo[NBCH - 2]) = S##b2; *(uint4*)(d_ + blo[NBCH - 1]) = S##b3; } } while (0)
; template <int NJ, class RowA>
; DI void gemm_main(f32x16 (&acc)[2][NJ], const bf16_t* __restrict__ A, RowA rowA, size_t kstrideA, int m0, int Mmax,
;                   const bf16_t* __restrict__ Bt, size_t ldb, int n0, int nk, char* smem) {
;     ...
;   __syncthreads();
;   G_LOAD(x0, 0, 0);
;   G_LOAD(x1, 0, 1);
;   G_STORE(0, x0, 0);
;   __syncthreads();
; #pragma unroll 1
;   for (int kt = 0; kt < nk; kt += 2) {
;     G_LOAD(x0, 0, (kt + 2 < nk ? kt + 2 : nk - 1));
;     G_COMPUTE(0);
;     G_STORE(1, x1, 0);
;     __syncthreads();
;     G_LOAD(x1, 0, (kt + 3 < nk ? kt + 3 : nk - 1));
;     G_COMPUTE(1);
;     G_STORE(0, x0, 0);
;     __syncthreads();
;   }
.LBB0_12:
	ds_read_b128 v[166:169], v0
	ds_read_b128 v[170:173], v139 offset:18432
	ds_read_b128 v[174:177], v139 offset:23040
	ds_read_b128 v[178:181], v0 offset:4608
	s_add_i32 s4, s3, 4
	s_min_u32 s4, s4, 15
	s_lshl_b32 s14, s4, 7
	v_lshl_add_u64 v[98:99], v[122:123], 0, s[14:15]
	v_lshl_add_u64 v[102:103], v[124:125], 0, s[14:15]
	v_lshl_add_u64 v[106:107], v[126:127], 0, s[14:15]
	v_lshl_add_u64 v[110:111], v[128:129], 0, s[14:15]
	v_lshl_add_u64 v[114:115], v[130:131], 0, s[14:15]
	v_lshl_add_u64 v[118:119], v[132:133], 0, s[14:15]
	s_add_i32 s3, s3, 2
	v_lshl_add_u64 v[158:159], v[134:135], 0, s[14:15]
	v_lshl_add_u64 v[160:161], v[136:137], 0, s[14:15]
	s_setprio 1
	ds_read_b128 v[182:185], v0 offset:32
	ds_read_b128 v[186:189], v139 offset:18464
	ds_read_b128 v[190:193], v139 offset:23072
	ds_read_b128 v[194:197], v0 offset:4640
	s_waitcnt lgkmcnt(4)
	v_mfma_f32_32x32x16_bf16 v[50:65], v[166:169], v[170:173], v[50:65]
	global_load_dwordx4 v[98:101], v[98:99], off
	v_mfma_f32_32x32x16_bf16 v[34:49], v[166:169], v[174:177], v[34:49]
	global_load_dwordx4 v[102:105], v[102:103], off
	v_mfma_f32_32x32x16_bf16 v[18:33], v[178:181], v[170:173], v[18:33]
	global_load_dwordx4 v[106:109], v[106:107], off
	v_mfma_f32_32x32x16_bf16 v[2:17], v[178:181], v[174:177], v[2:17]
	global_load_dwordx4 v[110:113], v[110:111], off
	ds_read_b128 v[166:169], v0 offset:64
	ds_read_b128 v[170:173], v139 offset:18496
	ds_read_b128 v[174:177], v139 offset:23104
	ds_read_b128 v[178:181], v0 offset:4672
	s_waitcnt lgkmcnt(4)
	v_mfma_f32_32x32x16_bf16 v[50:65], v[182:185], v[186:189], v[50:65]
	global_load_dwordx4 v[114:117], v[114:115], off
	v_mfma_f32_32x32x16_bf16 v[34:49], v[182:185], v[190:193], v[34:49]
	global_load_dwordx4 v[118:121], v[118:119], off
	v_mfma_f32_32x32x16_bf16 v[18:33], v[194:197], v[186:189], v[18:33]
	global_load_dwordx4 v[146:149], v[160:161], off
	v_mfma_f32_32x32x16_bf16 v[2:17], v[194:197], v[190:193], v[2:17]
	global_load_dwordx4 v[150:153], v[158:159], off
	ds_read_b128 v[182:185], v0 offset:96
	ds_read_b128 v[186:189], v139 offset:18528
	ds_read_b128 v[190:193], v139 offset:23136
	ds_read_b128 v[194:197], v0 offset:4704
	s_waitcnt lgkmcnt(4)
	v_mfma_f32_32x32x16_bf16 v[50:65], v[166:169], v[170:173], v[50:65]
	s_waitcnt vmcnt(8)
	ds_write_b128 v138, v[78:81] offset:36864
	v_mfma_f32_32x32x16_bf16 v[34:49], v[166:169], v[174:177], v[34:49]
	ds_write_b128 v140, v[86:89] offset:36864
	v_mfma_f32_32x32x16_bf16 v[18:33], v[178:181], v[170:173], v[18:33]
	ds_write_b128 v142, v[90:93] offset:36864
	v_mfma_f32_32x32x16_bf16 v[2:17], v[178:181], v[174:177], v[2:17]
	ds_write_b128 v144, v[94:97] offset:36864
	s_waitcnt lgkmcnt(4)
	v_mfma_f32_32x32x16_bf16 v[50:65], v[182:185], v[186:189], v[50:65]
	ds_write_b128 v138, v[74:77] offset:55296
	v_mfma_f32_32x32x16_bf16 v[34:49], v[182:185], v[190:193], v[34:49]
	ds_write_b128 v140, v[82:85] offset:55296
	v_mfma_f32_32x32x16_bf16 v[18:33], v[194:197], v[186:189], v[18:33]
	ds_write_b128 v142, v[66:69] offset:55296
	v_mfma_f32_32x32x16_bf16 v[2:17], v[194:197], v[190:193], v[2:17]
	ds_write_b128 v144, v[70:73] offset:55296
	s_setprio 0
	s_min_u32 s4, s3, 12
	s_lshl_b32 s14, s4, 7
	v_lshl_add_u64 v[66:67], v[122:123], 0, s[14:15]
	v_lshl_add_u64 v[68:69], v[124:125], 0, s[14:15]
	v_lshl_add_u64 v[70:71], v[126:127], 0, s[14:15]
	v_lshl_add_u64 v[72:73], v[128:129], 0, s[14:15]
	v_lshl_add_u64 v[74:75], v[130:131], 0, s[14:15]
	v_lshl_add_u64 v[82:83], v[132:133], 0, s[14:15]
	s_waitcnt lgkmcnt(0)
	s_barrier
	ds_read_b128 v[166:169], v0 offset:36864
	ds_read_b128 v[170:173], v139 offset:55296
	ds_read_b128 v[174:177], v139 offset:59904
	ds_read_b128 v[178:181], v0 offset:41472
	v_lshl_add_u64 v[154:155], v[134:135], 0, s[14:15]
	v_lshl_add_u64 v[156:157], v[136:137], 0, s[14:15]
	s_setprio 1
	ds_read_b128 v[182:185], v0 offset:36896
	ds_read_b128 v[186:189], v139 offset:55328
	ds_read_b128 v[190:193], v139 offset:59936
	ds_read_b128 v[194:197], v0 offset:41504
	s_waitcnt lgkmcnt(4)
	v_mfma_f32_32x32x16_bf16 v[50:65], v[166:169], v[170:173], v[50:65]
	global_load_dwordx4 v[78:81], v[66:67], off offset:384
	v_mfma_f32_32x32x16_bf16 v[34:49], v[166:169], v[174:177], v[34:49]
	global_load_dwordx4 v[86:89], v[68:69], off offset:384
	v_mfma_f32_32x32x16_bf16 v[18:33], v[178:181], v[170:173], v[18:33]
	global_load_dwordx4 v[90:93], v[70:71], off offset:384
	v_mfma_f32_32x32x16_bf16 v[2:17], v[178:181], v[174:177], v[2:17]
	global_load_dwordx4 v[94:97], v[72:73], off offset:384
	ds_read_b128 v[166:169], v0 offset:36928
	ds_read_b128 v[170:173], v139 offset:55360
	ds_read_b128 v[174:177], v139 offset:59968
	ds_read_b128 v[178:181], v0 offset:41536
	s_waitcnt lgkmcnt(4)
	v_mfma_f32_32x32x16_bf16 v[50:65], v[182:185], v[186:189], v[50:65]
	global_load_dwordx4 v[74:77], v[74:75], off offset:384
	v_mfma_f32_32x32x16_bf16 v[34:49], v[182:185], v[190:193], v[34:49]
	global_load_dwordx4 v[82:85], v[82:83], off offset:384
	v_mfma_f32_32x32x16_bf16 v[18:33], v[194:197], v[186:189], v[18:33]
	global_load_dwordx4 v[66:69], v[154:155], off offset:384
	v_mfma_f32_32x32x16_bf16 v[2:17], v[194:197], v[190:193], v[2:17]
	global_load_dwordx4 v[70:73], v[156:157], off offset:384
	ds_read_b128 v[182:185], v0 offset:36960
	ds_read_b128 v[186:189], v139 offset:55392
	ds_read_b128 v[190:193], v139 offset:60000
	ds_read_b128 v[194:197], v0 offset:41568
	s_waitcnt lgkmcnt(4)
	v_mfma_f32_32x32x16_bf16 v[50:65], v[166:169], v[170:173], v[50:65]
	s_waitcnt vmcnt(8)
	ds_write_b128 v138, v[98:101]
	v_mfma_f32_32x32x16_bf16 v[34:49], v[166:169], v[174:177], v[34:49]
	ds_write_b128 v140, v[102:105]
	v_mfma_f32_32x32x16_bf16 v[18:33], v[178:181], v[170:173], v[18:33]
	ds_write_b128 v142, v[106:109]
	v_mfma_f32_32x32x16_bf16 v[2:17], v[178:181], v[174:177], v[2:17]
	ds_write_b128 v144, v[110:113]
	s_waitcnt lgkmcnt(4)
	v_mfma_f32_32x32x16_bf16 v[50:65], v[182:185], v[186:189], v[50:65]
	ds_write_b128 v138, v[114:117] offset:18432
	v_mfma_f32_32x32x16_bf16 v[34:49], v[182:185], v[190:193], v[34:49]
	ds_write_b128 v140, v[118:121] offset:18432
	v_mfma_f32_32x32x16_bf16 v[18:33], v[194:197], v[186:189], v[18:33]
	ds_write_b128 v142, v[150:153] offset:18432
	v_mfma_f32_32x32x16_bf16 v[2:17], v[194:197], v[190:193], v[2:17]
	ds_write_b128 v144, v[146:149] offset:18432
	s_setprio 0
	s_cmp_lt_u32 s3, 14
	s_waitcnt lgkmcnt(0)
	s_barrier
; #define TIDX (tid_launder())
; DI int crow(int reg, int hh) { return (reg & 3) + 8 * (reg >> 2) + 4 * hh; }
; template <int NJ>
; DI void acc_to_ct(const f32x16 (&acc)[2][NJ], float* Ct) {
;   const int lane = TIDX & 63, wid = TIDX >> 6, wm = wid >> 1, wn = wid & 1;
;   const int r = lane & 31, hh = lane >> 5;
; #pragma unroll
;   for (int i = 0; i < 2; ++i)
; #pragma unroll
;     for (int j = 0; j < NJ; ++j)
; #pragma unroll
;       for (int e = 0; e < 16; ++e) Ct[(wm * 64 + i * 32 + crow(e, hh)) * 132 + wn * 32 * NJ + j * 32 + r] = acc[i][j][e];
;   __syncthreads();
; DI void outproj_tile(const Params& p, int l, int mt, int tn, char* smem) {
;     ...
;   const float* xo = l == 0 ? p.x_in : p.out;
;   {
;     const int tid = TIDX, c = (tid & 31) * 4, row0 = tid >> 5;
;     float4 xa[16];
; #pragma unroll
;     for (int q = 0; q < 16; ++q) xa[q] = *(const float4*)(xo + (size_t)(m0 + row0 + 8 * q) * 1024 + tn * 128 + c);
	s_cbranch_scc1 .LBB0_12
	v_mov_b32_e32 v0, v230
	s_waitcnt vmcnt(1)
	v_mov_b32_e32 v66, v230
	v_and_b32_e32 v67, 31, v0
	v_lshrrev_b32_e32 v0, 3, v0
	v_and_b32_e32 v0, 4, v0
	v_lshrrev_b32_e32 v68, 1, v66
	v_and_or_b32 v0, v68, s47, v0
	v_and_or_b32 v66, v66, 64, v67
	v_mul_lo_u32 v0, v0, s79
	v_lshl_add_u32 v0, v66, 2, v0
	ds_write2_b32 v0, v50, v34 offset1:32
	ds_write2_b32 v0, v51, v35 offset0:132 offset1:164
	v_add_u32_e32 v34, 0x400, v0
	ds_write2_b32 v34, v52, v36 offset0:8 offset1:40
	ds_write2_b32 v34, v53, v37 offset0:140 offset1:172
	v_add_u32_e32 v34, 0x1000, v0
	ds_write2_b32 v34, v54, v38 offset0:32 offset1:64
	ds_write2_b32 v34, v55, v39 offset0:164 offset1:196
	v_add_u32_e32 v34, 0x1400, v0
	ds_write2_b32 v34, v56, v40 offset0:40 offset1:72
	ds_write2_b32 v34, v57, v41 offset0:172 offset1:204
	v_add_u32_e32 v34, 0x2000, v0
	ds_write2_b32 v34, v58, v42 offset0:64 offset1:96
	ds_write2_b32 v34, v59, v43 offset0:196 offset1:228
	v_add_u32_e32 v34, 0x2400, v0
	ds_write2_b32 v34, v60, v44 offset0:72 offset1:104
	ds_write2_b32 v34, v61, v45 offset0:204 offset1:236
	v_add_u32_e32 v34, 0x3000, v0
	ds_write2_b32 v34, v62, v46 offset0:96 offset1:128
	v_add_u32_e32 v34, 0x3200, v0
	ds_write2_b32 v34, v63, v47 offset0:100 offset1:132
	v_add_u32_e32 v34, 0x3400, v0
	ds_write2_b32 v34, v64, v48 offset0:104 offset1:136
	v_add_u32_e32 v34, 0x3600, v0
	ds_write2_b32 v34, v65, v49 offset0:108 offset1:140
	v_add_u32_e32 v34, 0x4000, v0
	ds_write2_b32 v34, v18, v2 offset0:128 offset1:160
	v_add_u32_e32 v2, 0x4400, v0
	ds_write2_b32 v2, v19, v3 offset0:4 offset1:36
	ds_write2_b32 v2, v20, v4 offset0:136 offset1:168
	v_add_u32_e32 v2, 0x4800, v0
	ds_write2_b32 v2, v21, v5 offset0:12 offset1:44
	v_add_u32_e32 v2, 0x5000, v0
	ds_write2_b32 v2, v22, v6 offset0:160 offset1:192
	v_add_u32_e32 v2, 0x5400, v0
	ds_write2_b32 v2, v23, v7 offset0:36 offset1:68
	ds_write2_b32 v2, v24, v8 offset0:168 offset1:200
	v_add_u32_e32 v2, 0x5800, v0
	ds_write2_b32 v2, v25, v9 offset0:44 offset1:76
	v_add_u32_e32 v2, 0x6000, v0
	ds_write2_b32 v2, v26, v10 offset0:192 offset1:224
	v_add_u32_e32 v2, 0x6400, v0
	ds_write2_b32 v2, v27, v11 offset0:68 offset1:100
	ds_write2_b32 v2, v28, v12 offset0:200 offset1:232
	v_add_u32_e32 v2, 0x6800, v0
	ds_write2_b32 v2, v29, v13 offset0:76 offset1:108
	v_add_u32_e32 v2, 0x7200, v0
	ds_write2_b32 v2, v30, v14 offset0:96 offset1:128
	v_add_u32_e32 v2, 0x7400, v0
	ds_write2_b32 v2, v31, v15 offset0:100 offset1:132
	v_add_u32_e32 v2, 0x7600, v0
	v_add_u32_e32 v0, 0x7800, v0
	ds_write2_b32 v0, v33, v17 offset0:108 offset1:140
	v_mov_b32_e32 v0, v230
	ds_write2_b32 v2, v32, v16 offset0:104 offset1:136
	s_waitcnt lgkmcnt(0)
	s_barrier
	s_lshl_b32 s14, s2, 2
	v_ashrrev_i32_e32 v68, 5, v0
	v_readlane_b32 s2, v254, 3
	v_add_u32_e32 v2, s1, v68
	v_readlane_b32 s3, v254, 4
	s_add_u32 s2, s2, s14
	v_lshlrev_b32_e32 v0, 4, v0
	s_addc_u32 s3, s3, 0
	v_and_b32_e32 v0, 0x1f0, v0
	v_ashrrev_i32_e32 v3, 31, v2
	v_lshl_add_u64 v[4:5], s[2:3], 0, v[0:1]
	v_lshlrev_b64 v[8:9], 12, v[2:3]
	s_mov_b64 s[2:3], 0x18000
	v_lshl_add_u64 v[20:21], v[8:9], 0, s[2:3]
	s_mov_b64 s[2:3], 0x20000
	v_lshl_add_u64 v[24:25], v[8:9], 0, s[2:3]
	s_mov_b64 s[2:3], 0x28000
	v_lshl_add_u64 v[28:29], v[8:9], 0, s[2:3]
	s_mov_b64 s[2:3], 0x30000
	v_lshl_add_u64 v[32:33], v[8:9], 0, s[2:3]
	s_mov_b64 s[2:3], 0x38000
	v_lshl_add_u64 v[36:37], v[8:9], 0, s[2:3]
	s_mov_b64 s[2:3], 0x40000
	v_lshl_add_u64 v[40:41], v[8:9], 0, s[2:3]
	s_mov_b64 s[2:3], 0x48000
	v_lshl_add_u64 v[44:45], v[8:9], 0, s[2:3]
	s_mov_b64 s[2:3], 0x50000
	v_lshl_add_u64 v[48:49], v[8:9], 0, s[2:3]
	s_mov_b64 s[2:3], 0x58000
	v_lshl_add_u64 v[52:53], v[8:9], 0, s[2:3]
	s_mov_b64 s[2:3], 0x60000
	v_lshl_add_u64 v[56:57], v[8:9], 0, s[2:3]
	s_mov_b64 s[2:3], 0x68000
	v_lshl_add_u64 v[60:61], v[8:9], 0, s[2:3]
	s_mov_b64 s[2:3], 0x70000
	v_lshl_add_u64 v[64:65], v[8:9], 0, s[2:3]
	s_mov_b64 s[2:3], 0x78000
	v_readlane_b32 s16, v252, 9
	v_lshl_add_u64 v[12:13], v[8:9], 0, s[48:49]
	v_lshl_add_u64 v[16:17], v[8:9], 0, s[40:41]
	v_lshl_add_u64 v[66:67], v[8:9], 0, s[2:3]
	v_readlane_b32 s22, v252, 15
	v_readlane_b32 s23, v252, 16
	v_lshl_add_u64 v[62:63], v[4:5], 0, v[8:9]
	v_lshl_add_u64 v[58:59], v[4:5], 0, v[12:13]
	v_lshl_add_u64 v[54:55], v[4:5], 0, v[16:17]
	v_lshl_add_u64 v[50:51], v[4:5], 0, v[20:21]
	v_lshl_add_u64 v[46:47], v[4:5], 0, v[24:25]
	v_lshl_add_u64 v[42:43], v[4:5], 0, v[28:29]
	v_lshl_add_u64 v[38:39], v[4:5], 0, v[32:33]
	v_lshl_add_u64 v[34:35], v[4:5], 0, v[36:37]
	v_lshl_add_u64 v[30:31], v[4:5], 0, v[40:41]
	v_lshl_add_u64 v[26:27], v[4:5], 0, v[44:45]
	v_lshl_add_u64 v[22:23], v[4:5], 0, v[48:49]
	v_lshl_add_u64 v[18:19], v[4:5], 0, v[52:53]
	v_lshl_add_u64 v[14:15], v[4:5], 0, v[56:57]
	v_lshl_add_u64 v[10:11], v[4:5], 0, v[60:61]
	v_lshl_add_u64 v[6:7], v[4:5], 0, v[64:65]
	v_lshl_add_u64 v[2:3], v[4:5], 0, v[66:67]
	v_lshl_add_u64 v[4:5], s[22:23], 0, v[8:9]
	v_lshl_add_u64 v[4:5], v[4:5], 0, s[14:15]
	v_lshl_add_u64 v[96:97], v[4:5], 0, v[0:1]
	v_lshl_add_u64 v[4:5], s[22:23], 0, v[12:13]
	v_lshl_add_u64 v[4:5], v[4:5], 0, s[14:15]
	v_lshl_add_u64 v[94:95], v[4:5], 0, v[0:1]
	v_lshl_add_u64 v[4:5], s[22:23], 0, v[16:17]
	v_lshl_add_u64 v[4:5], v[4:5], 0, s[14:15]
	v_lshl_add_u64 v[92:93], v[4:5], 0, v[0:1]
	v_lshl_add_u64 v[4:5], s[22:23], 0, v[20:21]
	v_lshl_add_u64 v[4:5], v[4:5], 0, s[14:15]
	v_lshl_add_u64 v[90:91], v[4:5], 0, v[0:1]
	v_lshl_add_u64 v[4:5], s[22:23], 0, v[24:25]
	v_lshl_add_u64 v[4:5], v[4:5], 0, s[14:15]
	v_lshl_add_u64 v[88:89], v[4:5], 0, v[0:1]
	v_lshl_add_u64 v[4:5], s[22:23], 0, v[28:29]
	v_lshl_add_u64 v[4:5], v[4:5], 0, s[14:15]
	v_lshl_add_u64 v[86:87], v[4:5], 0, v[0:1]
	v_lshl_add_u64 v[4:5], s[22:23], 0, v[32:33]
	v_lshl_add_u64 v[4:5], v[4:5], 0, s[14:15]
	v_lshl_add_u64 v[84:85], v[4:5], 0, v[0:1]
	v_lshl_add_u64 v[4:5], s[22:23], 0, v[36:37]
	v_lshl_add_u64 v[4:5], v[4:5], 0, s[14:15]
	v_lshl_add_u64 v[82:83], v[4:5], 0, v[0:1]
	v_lshl_add_u64 v[4:5], s[22:23], 0, v[40:41]
	v_lshl_add_u64 v[4:5], v[4:5], 0, s[14:15]
	v_lshl_add_u64 v[80:81], v[4:5], 0, v[0:1]
	v_lshl_add_u64 v[4:5], s[22:23], 0, v[44:45]
	v_lshl_add_u64 v[4:5], v[4:5], 0, s[14:15]
	v_lshl_add_u64 v[78:79], v[4:5], 0, v[0:1]
	v_lshl_add_u64 v[4:5], s[22:23], 0, v[48:49]
	v_lshl_add_u64 v[4:5], v[4:5], 0, s[14:15]
	v_lshl_add_u64 v[76:77], v[4:5], 0, v[0:1]
	v_lshl_add_u64 v[4:5], s[22:23], 0, v[52:53]
	v_lshl_add_u64 v[4:5], v[4:5], 0, s[14:15]
	v_lshl_add_u64 v[74:75], v[4:5], 0, v[0:1]
	v_lshl_add_u64 v[4:5], s[22:23], 0, v[56:57]
	v_lshl_add_u64 v[4:5], v[4:5], 0, s[14:15]
	s_waitcnt vmcnt(0)
; #define TIDX (tid_launder())
; DI void outproj_tile(const Params& p, int l, int mt, int tn, char* smem) {
;     ...
;     const int tid = TIDX, c = (tid & 31) * 4, row0 = tid >> 5;
;     float4 xa[16];
; #pragma unroll
;     for (int q = 0; q < 16; ++q) xa[q] = *(const float4*)(xo + (size_t)(m0 + row0 + 8 * q) * 1024 + tn * 128 + c);
; #pragma unroll
;     for (int q = 0; q < 16; ++q) {
;       const float4 cc = *(const float4*)(Ct + (row0 + 8 * q) * 132 + c);
;       *(float4*)(p.out + (size_t)(m0 + row0 + 8 * q) * 1024 + tn * 128 + c) = make_float4(xa[q].x + cc.x, xa[q].y + cc.y, xa[q].z + cc.z, xa[q].w + cc.w);
;     }
;   }
;   __syncthreads();
; __global__ void __launch_bounds__(256, 2) mega(Params p, int ph_lo, int ph_hi) {
;     ...
;         for (int idx = blockIdx.x >> 3; idx < 256; idx += gridDim.x >> 3) { const int t = (blockIdx.x & 7) * 256 + idx; outproj_tile(p, l, t >> 3, t & 7, smem); }
	v_lshl_add_u64 v[72:73], v[4:5], 0, v[0:1]
	v_lshl_add_u64 v[4:5], s[22:23], 0, v[60:61]
	v_lshl_add_u64 v[4:5], v[4:5], 0, s[14:15]
	v_lshl_add_u64 v[70:71], v[4:5], 0, v[0:1]
	v_lshl_add_u64 v[4:5], s[22:23], 0, v[64:65]
	v_lshl_add_u64 v[4:5], v[4:5], 0, s[14:15]
	v_mad_u64_u32 v[98:99], s[2:3], v68, s79, v[0:1]
	v_lshl_add_u64 v[68:69], v[4:5], 0, v[0:1]
	v_lshl_add_u64 v[4:5], s[22:23], 0, v[66:67]
	v_lshl_add_u64 v[4:5], v[4:5], 0, s[14:15]
	v_lshl_add_u64 v[66:67], v[4:5], 0, v[0:1]
	global_load_dwordx4 v[2:5], v[2:3], off
	ds_read_b128 v[100:103], v98 offset:63360
	global_load_dwordx4 v[6:9], v[6:7], off
	v_readlane_b32 s1, v250, 60
	global_load_dwordx4 v[10:13], v[10:11], off
	s_add_i32 s0, s0, s1
	global_load_dwordx4 v[14:17], v[14:15], off
	s_cmpk_gt_u32 s0, 0xff
	global_load_dwordx4 v[18:21], v[18:19], off
	v_readlane_b32 s17, v252, 10
	global_load_dwordx4 v[22:25], v[22:23], off
	v_readlane_b32 s18, v252, 11
	global_load_dwordx4 v[26:29], v[26:27], off
	v_readlane_b32 s19, v252, 12
	global_load_dwordx4 v[30:33], v[30:31], off
	v_readlane_b32 s20, v252, 13
	global_load_dwordx4 v[34:37], v[34:35], off
	v_readlane_b32 s21, v252, 14
	global_load_dwordx4 v[38:41], v[38:39], off
	v_readlane_b32 s24, v252, 17
	global_load_dwordx4 v[42:45], v[42:43], off
	v_readlane_b32 s25, v252, 18
	global_load_dwordx4 v[46:49], v[46:47], off
	v_readlane_b32 s26, v252, 19
	global_load_dwordx4 v[50:53], v[50:51], off
	v_readlane_b32 s27, v252, 20
	global_load_dwordx4 v[54:57], v[54:55], off
	v_readlane_b32 s28, v252, 21
	global_load_dwordx4 v[58:61], v[58:59], off
	v_readlane_b32 s29, v252, 22
	global_load_dwordx4 v[62:65], v[62:63], off
	v_readlane_b32 s30, v252, 23
	v_readlane_b32 s31, v252, 24
	s_waitcnt vmcnt(15) lgkmcnt(0)
	v_pk_add_f32 v[2:3], v[2:3], v[100:101]
	v_pk_add_f32 v[4:5], v[4:5], v[102:103]
	ds_read_b128 v[100:103], v98 offset:59136
	s_waitcnt vmcnt(14) lgkmcnt(0)
	v_pk_add_f32 v[6:7], v[6:7], v[100:101]
	v_pk_add_f32 v[8:9], v[8:9], v[102:103]
	ds_read_b128 v[100:103], v98 offset:54912
	s_waitcnt vmcnt(13) lgkmcnt(0)
	v_pk_add_f32 v[10:11], v[10:11], v[100:101]
	v_pk_add_f32 v[12:13], v[12:13], v[102:103]
	ds_read_b128 v[100:103], v98 offset:50688
	s_waitcnt vmcnt(12) lgkmcnt(0)
	v_pk_add_f32 v[14:15], v[14:15], v[100:101]
	v_pk_add_f32 v[16:17], v[16:17], v[102:103]
	ds_read_b128 v[100:103], v98 offset:46464
	s_waitcnt vmcnt(11) lgkmcnt(0)
	v_pk_add_f32 v[18:19], v[18:19], v[100:101]
	v_pk_add_f32 v[20:21], v[20:21], v[102:103]
	ds_read_b128 v[100:103], v98 offset:42240
	s_waitcnt vmcnt(10) lgkmcnt(0)
	v_pk_add_f32 v[22:23], v[22:23], v[100:101]
	v_pk_add_f32 v[24:25], v[24:25], v[102:103]
	ds_read_b128 v[100:103], v98 offset:38016
	s_waitcnt vmcnt(9) lgkmcnt(0)
	v_pk_add_f32 v[26:27], v[26:27], v[100:101]
	v_pk_add_f32 v[28:29], v[28:29], v[102:103]
	ds_read_b128 v[100:103], v98 offset:33792
	s_waitcnt vmcnt(8) lgkmcnt(0)
	v_pk_add_f32 v[30:31], v[30:31], v[100:101]
	v_pk_add_f32 v[32:33], v[32:33], v[102:103]
	ds_read_b128 v[100:103], v98 offset:29568
	s_waitcnt vmcnt(7) lgkmcnt(0)
	v_pk_add_f32 v[34:35], v[34:35], v[100:101]
	v_pk_add_f32 v[36:37], v[36:37], v[102:103]
	ds_read_b128 v[100:103], v98 offset:25344
	s_waitcnt vmcnt(6) lgkmcnt(0)
	v_pk_add_f32 v[38:39], v[38:39], v[100:101]
	v_pk_add_f32 v[40:41], v[40:41], v[102:103]
	ds_read_b128 v[100:103], v98 offset:21120
	s_waitcnt vmcnt(5) lgkmcnt(0)
	v_pk_add_f32 v[42:43], v[42:43], v[100:101]
	v_pk_add_f32 v[44:45], v[44:45], v[102:103]
	ds_read_b128 v[100:103], v98 offset:16896
	s_waitcnt vmcnt(4) lgkmcnt(0)
	v_pk_add_f32 v[46:47], v[46:47], v[100:101]
	v_pk_add_f32 v[48:49], v[48:49], v[102:103]
	ds_read_b128 v[100:103], v98 offset:12672
	s_waitcnt vmcnt(3) lgkmcnt(0)
	v_pk_add_f32 v[50:51], v[50:51], v[100:101]
	v_pk_add_f32 v[52:53], v[52:53], v[102:103]
	ds_read_b128 v[100:103], v98 offset:8448
	s_waitcnt vmcnt(2) lgkmcnt(0)
	v_pk_add_f32 v[54:55], v[54:55], v[100:101]
	v_pk_add_f32 v[56:57], v[56:57], v[102:103]
	ds_read_b128 v[100:103], v98 offset:4224
	s_waitcnt vmcnt(1) lgkmcnt(0)
	v_pk_add_f32 v[58:59], v[58:59], v[100:101]
	ds_read_b128 v[98:101], v98
	v_pk_add_f32 v[60:61], v[60:61], v[102:103]
	s_waitcnt vmcnt(0) lgkmcnt(0)
	v_pk_add_f32 v[62:63], v[62:63], v[98:99]
	v_pk_add_f32 v[64:65], v[64:65], v[100:101]
	global_store_dwordx4 v[96:97], v[62:65], off
	global_store_dwordx4 v[94:95], v[58:61], off
	global_store_dwordx4 v[92:93], v[54:57], off
	global_store_dwordx4 v[90:91], v[50:53], off
	global_store_dwordx4 v[88:89], v[46:49], off
	global_store_dwordx4 v[86:87], v[42:45], off
	global_store_dwordx4 v[84:85], v[38:41], off
	global_store_dwordx4 v[82:83], v[34:37], off
	global_store_dwordx4 v[80:81], v[30:33], off
	global_store_dwordx4 v[78:79], v[26:29], off
	global_store_dwordx4 v[76:77], v[22:25], off
	global_store_dwordx4 v[74:75], v[18:21], off
	global_store_dwordx4 v[72:73], v[14:17], off
	global_store_dwordx4 v[70:71], v[10:13], off
	global_store_dwordx4 v[68:69], v[6:9], off
	global_store_dwordx4 v[66:67], v[2:5], off
	s_barrier
	s_cbranch_scc0 .LBB0_11

; #define G_STORE(ST, S, unused) do { char* d_ = smem + (ST) * STAGE; \
;     *(uint4*)(d_ + alo[0]) = S##a0; *(uint4*)(d_ + alo[1]) = S##a1; *(uint4*)(d_ + alo[2]) = S##a2; *(uint4*)(d_ + alo[3]) = S##a3; \
;     *(uint4*)(d_ + blo[0]) = S##b0; *(uint4*)(d_ + blo[1]) = S##b1; \
;     if (NBCH == 4) { *(uint4*)(d_ + blo[NBCH - 2]) = S##b2; *(uint4*)(d_ + blo[NBCH - 1]) = S##b3; } } while (0)
; template <int NJ, class RowA>
; DI void gemm_main(f32x16 (&acc)[2][NJ], const bf16_t* __restrict__ A, RowA rowA, size_t kstrideA, int m0, int Mmax,
;                   const bf16_t* __restrict__ Bt, size_t ldb, int n0, int nk, char* smem) {
;     ...
;   __syncthreads();
;   G_LOAD(x0, 0, 0);
;   G_LOAD(x1, 0, 1);
;   G_STORE(0, x0, 0);
;   __syncthreads();
; #pragma unroll 1
;   for (int kt = 0; kt < nk; kt += 2) {
;     G_LOAD(x0, 0, (kt + 2 < nk ? kt + 2 : nk - 1));
;     G_COMPUTE(0);
;     G_STORE(1, x1, 0);
;     __syncthreads();
;     G_LOAD(x1, 0, (kt + 3 < nk ? kt + 3 : nk - 1));
;     G_COMPUTE(1);
;     G_STORE(0, x0, 0);
;     __syncthreads();
;   }
; DI void merge_tile(const Params& p, int mt, int nt, char* smem) {
;     ...
;     gemm_main<1>(ag, p.h, RowLin{1024}, 64, m0, T_TOK, p.wt_in + (size_t)(4224 + x * 1024) * 1024, 1024, n0, 16, smem);
.LBB0_19:
	ds_read_b128 v[176:179], v0
	ds_read_b128 v[180:183], v71 offset:18432
	ds_read_b128 v[184:187], v0 offset:4608
	s_add_i32 s5, s4, 4
	s_min_u32 s5, s5, 15
	s_lshl_b32 s14, s5, 7
	v_lshl_add_u64 v[78:79], v[58:59], 0, s[14:15]
	v_lshl_add_u64 v[82:83], v[60:61], 0, s[14:15]
	v_lshl_add_u64 v[86:87], v[62:63], 0, s[14:15]
	v_lshl_add_u64 v[122:123], v[64:65], 0, s[14:15]
	v_lshl_add_u64 v[126:127], v[66:67], 0, s[14:15]
	v_lshl_add_u64 v[130:131], v[68:69], 0, s[14:15]
	s_add_i32 s4, s4, 2
	s_setprio 1
	ds_read_b128 v[188:191], v0 offset:32
	ds_read_b128 v[192:195], v71 offset:18464
	ds_read_b128 v[196:199], v0 offset:4640
	s_waitcnt lgkmcnt(3)
	v_mfma_f32_32x32x16_bf16 v[18:33], v[176:179], v[180:183], v[18:33]
	global_load_dwordx4 v[78:81], v[78:79], off
	s_nop 0
	global_load_dwordx4 v[82:85], v[82:83], off
	v_mfma_f32_32x32x16_bf16 v[2:17], v[184:187], v[180:183], v[2:17]
	global_load_dwordx4 v[86:89], v[86:87], off
	ds_read_b128 v[176:179], v0 offset:64
	ds_read_b128 v[180:183], v71 offset:18496
	ds_read_b128 v[184:187], v0 offset:4672
	s_waitcnt lgkmcnt(3)
	v_mfma_f32_32x32x16_bf16 v[18:33], v[188:191], v[192:195], v[18:33]
	global_load_dwordx4 v[122:125], v[122:123], off
	s_nop 0
	global_load_dwordx4 v[126:129], v[126:127], off
	v_mfma_f32_32x32x16_bf16 v[2:17], v[196:199], v[192:195], v[2:17]
	global_load_dwordx4 v[130:133], v[130:131], off
	ds_read_b128 v[188:191], v0 offset:96
	ds_read_b128 v[192:195], v71 offset:18528
	ds_read_b128 v[196:199], v0 offset:4704
	s_waitcnt lgkmcnt(3)
	v_mfma_f32_32x32x16_bf16 v[18:33], v[176:179], v[180:183], v[18:33]
	s_waitcnt vmcnt(6)
	ds_write_b128 v70, v[34:37] offset:27648
	ds_write_b128 v72, v[38:41] offset:27648
	v_mfma_f32_32x32x16_bf16 v[2:17], v[184:187], v[180:183], v[2:17]
	ds_write_b128 v74, v[42:45] offset:27648
	s_waitcnt lgkmcnt(3)
	v_mfma_f32_32x32x16_bf16 v[18:33], v[188:191], v[192:195], v[18:33]
	ds_write_b128 v76, v[54:57] offset:27648
	ds_write_b128 v70, v[46:49] offset:46080
	v_mfma_f32_32x32x16_bf16 v[2:17], v[196:199], v[192:195], v[2:17]
	ds_write_b128 v72, v[50:53] offset:46080
	s_setprio 0
	s_min_u32 s5, s4, 12
	s_lshl_b32 s14, s5, 7
	v_lshl_add_u64 v[34:35], v[58:59], 0, s[14:15]
	v_lshl_add_u64 v[38:39], v[60:61], 0, s[14:15]
	v_lshl_add_u64 v[42:43], v[62:63], 0, s[14:15]
	v_lshl_add_u64 v[46:47], v[64:65], 0, s[14:15]
	v_lshl_add_u64 v[48:49], v[66:67], 0, s[14:15]
	v_lshl_add_u64 v[50:51], v[68:69], 0, s[14:15]
	s_waitcnt lgkmcnt(0)
	s_barrier
	ds_read_b128 v[176:179], v0 offset:27648
	ds_read_b128 v[180:183], v71 offset:46080
	ds_read_b128 v[184:187], v0 offset:32256
	s_setprio 1
	ds_read_b128 v[188:191], v0 offset:27680
	ds_read_b128 v[192:195], v71 offset:46112
	ds_read_b128 v[196:199], v0 offset:32288
	s_waitcnt lgkmcnt(3)
	v_mfma_f32_32x32x16_bf16 v[18:33], v[176:179], v[180:183], v[18:33]
	global_load_dwordx4 v[34:37], v[34:35], off offset:384
	s_nop 0
	global_load_dwordx4 v[38:41], v[38:39], off offset:384
	v_mfma_f32_32x32x16_bf16 v[2:17], v[184:187], v[180:183], v[2:17]
	global_load_dwordx4 v[42:45], v[42:43], off offset:384
	ds_read_b128 v[176:179], v0 offset:27712
	ds_read_b128 v[180:183], v71 offset:46144
	ds_read_b128 v[184:187], v0 offset:32320
	s_waitcnt lgkmcnt(3)
	v_mfma_f32_32x32x16_bf16 v[18:33], v[188:191], v[192:195], v[18:33]
	global_load_dwordx4 v[54:57], v[46:47], off offset:384
	s_nop 0
	global_load_dwordx4 v[46:49], v[48:49], off offset:384
	v_mfma_f32_32x32x16_bf16 v[2:17], v[196:199], v[192:195], v[2:17]
	global_load_dwordx4 v[50:53], v[50:51], off offset:384
	ds_read_b128 v[188:191], v0 offset:27744
	ds_read_b128 v[192:195], v71 offset:46176
	ds_read_b128 v[196:199], v0 offset:32352
	s_waitcnt lgkmcnt(3)
	v_mfma_f32_32x32x16_bf16 v[18:33], v[176:179], v[180:183], v[18:33]
	s_waitcnt vmcnt(6)
	ds_write_b128 v70, v[78:81]
	ds_write_b128 v72, v[82:85]
	v_mfma_f32_32x32x16_bf16 v[2:17], v[184:187], v[180:183], v[2:17]
	ds_write_b128 v74, v[86:89]
	s_waitcnt lgkmcnt(3)
	v_mfma_f32_32x32x16_bf16 v[18:33], v[188:191], v[192:195], v[18:33]
	ds_write_b128 v76, v[122:125]
	ds_write_b128 v70, v[126:129] offset:18432
	v_mfma_f32_32x32x16_bf16 v[2:17], v[196:199], v[192:195], v[2:17]
	ds_write_b128 v72, v[130:133] offset:18432
	s_setprio 0
	s_cmp_lt_u32 s4, 14
	s_waitcnt lgkmcnt(0)
	s_barrier
	s_cbranch_scc1 .LBB0_19
	s_cmp_eq_u32 s3, 1
	s_cselect_b32 s5, s42, 0x300
	s_cselect_b32 s4, 8, 4
	s_cmp_lg_u32 s3, 0
	v_mov_b32_e32 v58, v230
	s_cselect_b32 s5, s5, 0
	v_readlane_b32 s16, v252, 57
	s_lshl_b32 s5, s5, 1
	v_ashrrev_i32_e32 v59, 3, v58
	v_readlane_b32 s28, v253, 5
	s_waitcnt vmcnt(5)
	v_add_u32_e32 v36, s1, v59
	v_readlane_b32 s29, v253, 6
	s_add_u32 s6, s28, s5
	v_lshlrev_b32_e32 v0, 4, v58
	v_min_i32_e32 v36, 0x7fff, v36
	s_addc_u32 s7, s29, 0
	v_and_b32_e32 v0, 0x70, v0
	v_ashrrev_i32_e32 v37, 31, v36
	v_lshl_add_u64 v[34:35], s[6:7], 0, v[0:1]
	v_lshlrev_b64 v[36:37], 11, v[36:37]
	v_lshl_add_u64 v[122:123], v[34:35], 0, v[36:37]
	v_add_u32_e32 v36, 0x100, v58
	v_ashrrev_i32_e32 v60, 3, v36
	v_add_u32_e32 v36, s1, v60
	v_min_i32_e32 v36, 0x7fff, v36
	v_ashrrev_i32_e32 v37, 31, v36
	v_lshlrev_b64 v[36:37], 11, v[36:37]
	v_lshl_add_u64 v[124:125], v[34:35], 0, v[36:37]
	v_add_u32_e32 v36, 0x200, v58
	v_ashrrev_i32_e32 v61, 3, v36
	v_add_u32_e32 v36, s1, v61
	v_min_i32_e32 v36, 0x7fff, v36
	v_ashrrev_i32_e32 v37, 31, v36
	v_lshlrev_b64 v[36:37], 11, v[36:37]
	v_lshl_add_u64 v[126:127], v[34:35], 0, v[36:37]
	v_add_u32_e32 v36, 0x300, v58
	v_ashrrev_i32_e32 v62, 3, v36
	v_add_u32_e32 v36, s1, v62
	v_min_i32_e32 v36, 0x7fff, v36
	v_ashrrev_i32_e32 v37, 31, v36
	v_lshlrev_b64 v[36:37], 11, v[36:37]
	v_readlane_b32 s17, v252, 58
	s_add_u32 s8, s16, s5
	v_lshl_add_u64 v[128:129], v[34:35], 0, v[36:37]
	v_add_u32_e32 v36, s2, v59
	s_addc_u32 s9, s17, 0
	v_ashrrev_i32_e32 v37, 31, v36
	v_lshl_add_u64 v[34:35], s[8:9], 0, v[0:1]
	v_lshlrev_b64 v[36:37], 11, v[36:37]
	v_lshl_add_u64 v[130:131], v[34:35], 0, v[36:37]
	v_add_u32_e32 v36, s2, v60
	v_ashrrev_i32_e32 v37, 31, v36
	v_lshlrev_b64 v[36:37], 11, v[36:37]
	v_lshl_add_u64 v[132:133], v[34:35], 0, v[36:37]
	s_barrier
; #define G_STORE(ST, S, unused) do { char* d_ = smem + (ST) * STAGE; \
;     *(uint4*)(d_ + alo[0]) = S##a0; *(uint4*)(d_ + alo[1]) = S##a1; *(uint4*)(d_ + alo[2]) = S##a2; *(uint4*)(d_ + alo[3]) = S##a3; \
;     *(uint4*)(d_ + blo[0]) = S##b0; *(uint4*)(d_ + blo[1]) = S##b1; \
;     if (NBCH == 4) { *(uint4*)(d_ + blo[NBCH - 2]) = S##b2; *(uint4*)(d_ + blo[NBCH - 1]) = S##b3; } } while (0)
; template <int NJ, class RowA>
; DI void gemm_main(f32x16 (&acc)[2][NJ], const bf16_t* __restrict__ A, RowA rowA, size_t kstrideA, int m0, int Mmax,
;                   const bf16_t* __restrict__ Bt, size_t ldb, int n0, int nk, char* smem) {
;     ...
; #pragma unroll
;   for (int i = 0; i < 4; ++i) {
;     const int c = tid + 256 * i, row = c >> 3, kc = c & 7;
;     int m = m0 + row; m = m < Mmax ? m : Mmax - 1;
;     ap[i] = A + rowA(m) + kc * 8; alo[i] = row * 144 + kc * 16;
;   }
; #pragma unroll
;   for (int i = 0; i < NBCH; ++i) {
;     const int c = tid + 256 * i, row = c >> 3, kc = c & 7;
;     bp[i] = Bt + (size_t)(n0 + row) * ldb + kc * 8; blo[i] = 128 * 144 + row * 144 + kc * 16;
;   }
; #pragma unroll
;   for (int i = 0; i < 2; ++i)
; #pragma unroll
;     for (int j = 0; j < NJ; ++j)
; #pragma unroll
;       for (int e = 0; e < 16; ++e) acc[i][j][e] = 0.f;
;   uint4 x0a0, x0a1, x0a2, x0a3, x0b0, x0b1, x0b2, x0b3, x1a0, x1a1, x1a2, x1a3, x1b0, x1b1, x1b2, x1b3;
;   x0b2 = x0b3 = x1b2 = x1b3 = make_uint4(0, 0, 0, 0);
;     ...
;   __syncthreads();
;   G_LOAD(x0, 0, 0);
;   G_LOAD(x1, 0, 1);
;   G_STORE(0, x0, 0);
;   __syncthreads();
; #pragma unroll 1
;   for (int kt = 0; kt < nk; kt += 2) {
;     G_LOAD(x0, 0, (kt + 2 < nk ? kt + 2 : nk - 1));
;     G_COMPUTE(0);
;     G_STORE(1, x1, 0);
;     __syncthreads();
;     G_LOAD(x1, 0, (kt + 3 < nk ? kt + 3 : nk - 1));
;     G_COMPUTE(1);
;     G_STORE(0, x0, 0);
;     __syncthreads();
;   }
; DI void merge_tile(const Params& p, int mt, int nt, char* smem) {
;     ...
;     gemm_main<1>(ap, p.projZ + koff, RowLin{LDA_Z}, 64, m0, T_TOK, p.wt_br + koff, 1024, n0, nkp, smem);
	global_load_dwordx4 v[34:37], v[122:123], off
	global_load_dwordx4 v[38:41], v[124:125], off
	global_load_dwordx4 v[42:45], v[126:127], off
	global_load_dwordx4 v[46:49], v[128:129], off
	global_load_dwordx4 v[50:53], v[130:131], off
	global_load_dwordx4 v[54:57], v[132:133], off
	global_load_dwordx4 v[66:69], v[122:123], off offset:128
	global_load_dwordx4 v[70:73], v[124:125], off offset:128
	global_load_dwordx4 v[74:77], v[126:127], off offset:128
	global_load_dwordx4 v[78:81], v[128:129], off offset:128
	global_load_dwordx4 v[82:85], v[130:131], off offset:128
	global_load_dwordx4 v[86:89], v[132:133], off offset:128
	v_and_b32_e32 v63, 31, v58
	v_lshrrev_b32_e32 v58, 1, v58
	v_and_or_b32 v64, v58, s47, v63
	v_and_b32_e32 v65, 16, v58
	v_and_or_b32 v58, v58, 32, v63
	v_mad_u64_u32 v[134:135], s[6:7], v59, s76, v[0:1]
	v_mad_u64_u32 v[136:137], s[6:7], v60, s76, v[0:1]
	v_mad_u64_u32 v[138:139], s[6:7], v61, s76, v[0:1]
	v_mad_u64_u32 v[140:141], s[6:7], v62, s76, v[0:1]
	v_mul_u32_u24_e32 v58, 0x90, v58
	v_mul_lo_u32 v0, v64, s76
	s_mov_b32 s5, 3
	s_add_i32 s6, s4, -1
	v_add_u32_e32 v0, v65, v0
	v_add_u32_e32 v135, v58, v65
	v_readlane_b32 s18, v252, 59
	v_readlane_b32 s19, v252, 60
	v_readlane_b32 s20, v252, 61
	v_readlane_b32 s21, v252, 62
	v_readlane_b32 s22, v252, 63
	v_readlane_b32 s23, v253, 0
	v_readlane_b32 s24, v253, 1
	v_readlane_b32 s25, v253, 2
	v_readlane_b32 s26, v253, 3
	v_readlane_b32 s27, v253, 4
	v_readlane_b32 s30, v253, 7
	v_readlane_b32 s31, v253, 8
	s_waitcnt vmcnt(11)
	ds_write_b128 v134, v[34:37]
	s_waitcnt vmcnt(10)
	ds_write_b128 v136, v[38:41]
	s_waitcnt vmcnt(9)
	ds_write_b128 v138, v[42:45]
	s_waitcnt vmcnt(8)
	ds_write_b128 v140, v[46:49]
	s_waitcnt vmcnt(7)
	ds_write_b128 v134, v[50:53] offset:18432
	s_waitcnt vmcnt(6)
	ds_write_b128 v136, v[54:57] offset:18432
	v_mov_b32_e32 v34, 0
	v_mov_b32_e32 v35, v34
	v_mov_b32_e32 v36, v34
	v_mov_b32_e32 v37, v34
	v_mov_b32_e32 v38, v34
	v_mov_b32_e32 v39, v34
	v_mov_b32_e32 v40, v34
	v_mov_b32_e32 v41, v34
	v_mov_b32_e32 v42, v34
	v_mov_b32_e32 v43, v34
	v_mov_b32_e32 v44, v34
	v_mov_b32_e32 v45, v34
	v_mov_b32_e32 v46, v34
	v_mov_b32_e32 v47, v34
	v_mov_b32_e32 v48, v34
	v_mov_b32_e32 v49, v34
	v_mov_b32_e32 v50, v34
	v_mov_b32_e32 v51, v34
	v_mov_b32_e32 v52, v34
	v_mov_b32_e32 v53, v34
	v_mov_b32_e32 v54, v34
	v_mov_b32_e32 v55, v34
	v_mov_b32_e32 v56, v34
	v_mov_b32_e32 v57, v34
	v_mov_b32_e32 v58, v34
	v_mov_b32_e32 v59, v34
	v_mov_b32_e32 v60, v34
	v_mov_b32_e32 v61, v34
	v_mov_b32_e32 v62, v34
	v_mov_b32_e32 v63, v34
	v_mov_b32_e32 v64, v34
	v_mov_b32_e32 v65, v34
	s_waitcnt lgkmcnt(0)
	s_barrier
.LBB0_21:
	ds_read_b128 v[176:179], v0
	ds_read_b128 v[180:183], v135 offset:18432
	ds_read_b128 v[184:187], v0 offset:4608
	s_add_i32 s7, s5, -1
	s_min_u32 s14, s7, s6
	s_lshl_b64 s[8:9], s[14:15], 7
	v_lshl_add_u64 v[144:145], v[122:123], 0, s[8:9]
	v_lshl_add_u64 v[148:149], v[124:125], 0, s[8:9]
	v_lshl_add_u64 v[152:153], v[126:127], 0, s[8:9]
	v_lshl_add_u64 v[156:157], v[128:129], 0, s[8:9]
	v_lshl_add_u64 v[160:161], v[130:131], 0, s[8:9]
	v_lshl_add_u64 v[164:165], v[132:133], 0, s[8:9]
	s_setprio 1
	ds_read_b128 v[188:191], v0 offset:32
	ds_read_b128 v[192:195], v135 offset:18464
	ds_read_b128 v[196:199], v0 offset:4640
	s_waitcnt lgkmcnt(3)
	v_mfma_f32_32x32x16_bf16 v[50:65], v[176:179], v[180:183], v[50:65]
	global_load_dwordx4 v[144:147], v[144:145], off
	s_nop 0
	global_load_dwordx4 v[148:151], v[148:149], off
	v_mfma_f32_32x32x16_bf16 v[34:49], v[184:187], v[180:183], v[34:49]
	global_load_dwordx4 v[152:155], v[152:153], off
	ds_read_b128 v[176:179], v0 offset:64
	ds_read_b128 v[180:183], v135 offset:18496
	ds_read_b128 v[184:187], v0 offset:4672
	s_waitcnt lgkmcnt(3)
	v_mfma_f32_32x32x16_bf16 v[50:65], v[188:191], v[192:195], v[50:65]
	global_load_dwordx4 v[156:159], v[156:157], off
	s_nop 0
	global_load_dwordx4 v[160:163], v[160:161], off
	v_mfma_f32_32x32x16_bf16 v[34:49], v[196:199], v[192:195], v[34:49]
	global_load_dwordx4 v[164:167], v[164:165], off
	ds_read_b128 v[188:191], v0 offset:96
	ds_read_b128 v[192:195], v135 offset:18528
	ds_read_b128 v[196:199], v0 offset:4704
	s_waitcnt lgkmcnt(3)
	v_mfma_f32_32x32x16_bf16 v[50:65], v[176:179], v[180:183], v[50:65]
	s_waitcnt vmcnt(6)
	ds_write_b128 v134, v[66:69] offset:27648
	ds_write_b128 v136, v[70:73] offset:27648
	v_mfma_f32_32x32x16_bf16 v[34:49], v[184:187], v[180:183], v[34:49]
	ds_write_b128 v138, v[74:77] offset:27648
	s_waitcnt lgkmcnt(3)
	v_mfma_f32_32x32x16_bf16 v[50:65], v[188:191], v[192:195], v[50:65]
	ds_write_b128 v140, v[78:81] offset:27648
	ds_write_b128 v134, v[82:85] offset:46080
	v_mfma_f32_32x32x16_bf16 v[34:49], v[196:199], v[192:195], v[34:49]
	ds_write_b128 v136, v[86:89] offset:46080
	s_setprio 0
	s_min_u32 s14, s5, s6
	s_lshl_b64 s[8:9], s[14:15], 7
	v_lshl_add_u64 v[66:67], v[122:123], 0, s[8:9]
	v_lshl_add_u64 v[70:71], v[124:125], 0, s[8:9]
	v_lshl_add_u64 v[74:75], v[126:127], 0, s[8:9]
	v_lshl_add_u64 v[78:79], v[128:129], 0, s[8:9]
	v_lshl_add_u64 v[82:83], v[130:131], 0, s[8:9]
	v_lshl_add_u64 v[86:87], v[132:133], 0, s[8:9]
	s_waitcnt lgkmcnt(0)
	s_barrier
; DI float sigmoidf(float x) { return __builtin_amdgcn_rcpf(1.f + __expf(-x)); }
; #define G_STORE(ST, S, unused) do { char* d_ = smem + (ST) * STAGE; \
;     *(uint4*)(d_ + alo[0]) = S##a0; *(uint4*)(d_ + alo[1]) = S##a1; *(uint4*)(d_ + alo[2]) = S##a2; *(uint4*)(d_ + alo[3]) = S##a3; \
;     *(uint4*)(d_ + blo[0]) = S##b0; *(uint4*)(d_ + blo[1]) = S##b1; \
;     if (NBCH == 4) { *(uint4*)(d_ + blo[NBCH - 2]) = S##b2; *(uint4*)(d_ + blo[NBCH - 1]) = S##b3; } } while (0)
; template <int NJ, class RowA>
; DI void gemm_main(f32x16 (&acc)[2][NJ], const bf16_t* __restrict__ A, RowA rowA, size_t kstrideA, int m0, int Mmax,
;                   const bf16_t* __restrict__ Bt, size_t ldb, int n0, int nk, char* smem) {
;     ...
;   __syncthreads();
;   G_LOAD(x0, 0, 0);
;   G_LOAD(x1, 0, 1);
;   G_STORE(0, x0, 0);
;   __syncthreads();
; #pragma unroll 1
;   for (int kt = 0; kt < nk; kt += 2) {
;     G_LOAD(x0, 0, (kt + 2 < nk ? kt + 2 : nk - 1));
;     G_COMPUTE(0);
;     G_STORE(1, x1, 0);
;     __syncthreads();
;     G_LOAD(x1, 0, (kt + 3 < nk ? kt + 3 : nk - 1));
;     G_COMPUTE(1);
;     G_STORE(0, x0, 0);
;     __syncthreads();
;   }
; DI void merge_tile(const Params& p, int mt, int nt, char* smem) {
;     ...
; #pragma unroll
;     for (int i = 0; i < 2; ++i)
; #pragma unroll
;       for (int e = 0; e < 16; ++e) mac[i][0][e] += sigmoidf(ag[i][0][e]) * ap[i][0][e];
	ds_read_b128 v[176:179], v0 offset:27648
	ds_read_b128 v[180:183], v135 offset:46080
	ds_read_b128 v[184:187], v0 offset:32256
	s_setprio 1
	ds_read_b128 v[188:191], v0 offset:27680
	ds_read_b128 v[192:195], v135 offset:46112
	ds_read_b128 v[196:199], v0 offset:32288
	s_waitcnt lgkmcnt(3)
	v_mfma_f32_32x32x16_bf16 v[50:65], v[176:179], v[180:183], v[50:65]
	global_load_dwordx4 v[66:69], v[66:67], off
	s_nop 0
	global_load_dwordx4 v[70:73], v[70:71], off
	v_mfma_f32_32x32x16_bf16 v[34:49], v[184:187], v[180:183], v[34:49]
	global_load_dwordx4 v[74:77], v[74:75], off
	ds_read_b128 v[176:179], v0 offset:27712
	ds_read_b128 v[180:183], v135 offset:46144
	ds_read_b128 v[184:187], v0 offset:32320
	s_waitcnt lgkmcnt(3)
	v_mfma_f32_32x32x16_bf16 v[50:65], v[188:191], v[192:195], v[50:65]
	global_load_dwordx4 v[78:81], v[78:79], off
	s_nop 0
	global_load_dwordx4 v[82:85], v[82:83], off
	v_mfma_f32_32x32x16_bf16 v[34:49], v[196:199], v[192:195], v[34:49]
	global_load_dwordx4 v[86:89], v[86:87], off
	ds_read_b128 v[188:191], v0 offset:27744
	ds_read_b128 v[192:195], v135 offset:46176
	ds_read_b128 v[196:199], v0 offset:32352
	s_waitcnt lgkmcnt(3)
	v_mfma_f32_32x32x16_bf16 v[50:65], v[176:179], v[180:183], v[50:65]
	s_waitcnt vmcnt(6)
	ds_write_b128 v134, v[144:147]
	ds_write_b128 v136, v[148:151]
	v_mfma_f32_32x32x16_bf16 v[34:49], v[184:187], v[180:183], v[34:49]
	ds_write_b128 v138, v[152:155]
	s_waitcnt lgkmcnt(3)
	v_mfma_f32_32x32x16_bf16 v[50:65], v[188:191], v[192:195], v[50:65]
	ds_write_b128 v140, v[156:159]
	ds_write_b128 v134, v[160:163] offset:18432
	v_mfma_f32_32x32x16_bf16 v[34:49], v[196:199], v[192:195], v[34:49]
	ds_write_b128 v136, v[164:167] offset:18432
	s_setprio 0
	s_add_i32 s5, s5, 2
	s_cmp_lt_u32 s7, s4
	s_waitcnt lgkmcnt(0)
	s_barrier
	s_cbranch_scc1 .LBB0_21
	v_mul_f32_e32 v0, 0xbfb8aa3b, v18
	v_exp_f32_e32 v0, v0
	v_mul_f32_e32 v18, 0xbfb8aa3b, v19
	v_exp_f32_e32 v18, v18
	s_add_i32 s3, s3, 1
	v_add_f32_e32 v0, 1.0, v0
	s_cmp_lg_u32 s3, 3
	v_add_f32_e32 v19, 1.0, v18
	v_rcp_f32_e32 v18, v0
	v_mul_f32_e32 v0, 0xbfb8aa3b, v20
	v_exp_f32_e32 v0, v0
	v_mul_f32_e32 v20, 0xbfb8aa3b, v21
	v_rcp_f32_e32 v19, v19
	v_exp_f32_e32 v20, v20
	v_add_f32_e32 v0, 1.0, v0
	v_pk_fma_f32 v[120:121], v[18:19], v[50:51], v[120:121]
	v_rcp_f32_e32 v18, v0
	v_add_f32_e32 v0, 1.0, v20
	v_rcp_f32_e32 v19, v0
	v_mul_f32_e32 v0, 0xbfb8aa3b, v22
	v_exp_f32_e32 v0, v0
	v_mul_f32_e32 v20, 0xbfb8aa3b, v23
	v_exp_f32_e32 v20, v20
	v_pk_fma_f32 v[118:119], v[18:19], v[52:53], v[118:119]
	v_add_f32_e32 v0, 1.0, v0
	v_rcp_f32_e32 v18, v0
	v_add_f32_e32 v0, 1.0, v20
	v_rcp_f32_e32 v19, v0
	v_mul_f32_e32 v0, 0xbfb8aa3b, v24
	v_exp_f32_e32 v0, v0
	v_mul_f32_e32 v20, 0xbfb8aa3b, v25
	v_exp_f32_e32 v20, v20
	v_pk_fma_f32 v[116:117], v[18:19], v[54:55], v[116:117]
	v_add_f32_e32 v0, 1.0, v0
	v_rcp_f32_e32 v18, v0
	v_add_f32_e32 v0, 1.0, v20
	v_rcp_f32_e32 v19, v0
	v_mul_f32_e32 v0, 0xbfb8aa3b, v26
	v_exp_f32_e32 v0, v0
	v_mul_f32_e32 v20, 0xbfb8aa3b, v27
	v_exp_f32_e32 v20, v20
	v_pk_fma_f32 v[114:115], v[18:19], v[56:57], v[114:115]
	v_add_f32_e32 v0, 1.0, v0
	v_rcp_f32_e32 v18, v0
	v_add_f32_e32 v0, 1.0, v20
	v_rcp_f32_e32 v19, v0
	v_mul_f32_e32 v0, 0xbfb8aa3b, v28
	v_exp_f32_e32 v0, v0
	v_mul_f32_e32 v20, 0xbfb8aa3b, v29
	v_exp_f32_e32 v20, v20
	v_pk_fma_f32 v[112:113], v[18:19], v[58:59], v[112:113]
	v_add_f32_e32 v0, 1.0, v0
	v_rcp_f32_e32 v18, v0
	v_add_f32_e32 v0, 1.0, v20
	v_rcp_f32_e32 v19, v0
	v_mul_f32_e32 v0, 0xbfb8aa3b, v30
	v_exp_f32_e32 v0, v0
	v_mul_f32_e32 v20, 0xbfb8aa3b, v31
	v_exp_f32_e32 v20, v20
	v_pk_fma_f32 v[110:111], v[18:19], v[60:61], v[110:111]
	v_add_f32_e32 v0, 1.0, v0
	v_rcp_f32_e32 v18, v0
	v_add_f32_e32 v0, 1.0, v20
	v_rcp_f32_e32 v19, v0
	v_mul_f32_e32 v0, 0xbfb8aa3b, v32
	v_exp_f32_e32 v0, v0
	v_mul_f32_e32 v20, 0xbfb8aa3b, v33
	v_exp_f32_e32 v20, v20
	v_pk_fma_f32 v[108:109], v[18:19], v[62:63], v[108:109]
	v_add_f32_e32 v0, 1.0, v0
	v_rcp_f32_e32 v18, v0
	v_add_f32_e32 v0, 1.0, v20
	v_rcp_f32_e32 v19, v0
	v_mul_f32_e32 v0, 0xbfb8aa3b, v2
	v_exp_f32_e32 v0, v0
	v_mul_f32_e32 v2, 0xbfb8aa3b, v3
	v_exp_f32_e32 v3, v2
	v_pk_fma_f32 v[106:107], v[18:19], v[64:65], v[106:107]
	v_add_f32_e32 v0, 1.0, v0
	v_rcp_f32_e32 v2, v0
	v_add_f32_e32 v0, 1.0, v3
	v_rcp_f32_e32 v3, v0
	v_mul_f32_e32 v0, 0xbfb8aa3b, v4
	v_exp_f32_e32 v0, v0
	v_mul_f32_e32 v4, 0xbfb8aa3b, v5
	v_exp_f32_e32 v4, v4
	v_pk_fma_f32 v[104:105], v[2:3], v[34:35], v[104:105]
	v_add_f32_e32 v0, 1.0, v0
	v_rcp_f32_e32 v2, v0
	v_add_f32_e32 v0, 1.0, v4
	v_rcp_f32_e32 v3, v0
	v_mul_f32_e32 v0, 0xbfb8aa3b, v6
	v_exp_f32_e32 v0, v0
	v_mul_f32_e32 v4, 0xbfb8aa3b, v7
	v_exp_f32_e32 v4, v4
	v_pk_fma_f32 v[102:103], v[2:3], v[36:37], v[102:103]
	v_add_f32_e32 v0, 1.0, v0
	v_rcp_f32_e32 v2, v0
	v_add_f32_e32 v0, 1.0, v4
	v_rcp_f32_e32 v3, v0
	v_mul_f32_e32 v0, 0xbfb8aa3b, v8
	v_exp_f32_e32 v0, v0
	v_mul_f32_e32 v4, 0xbfb8aa3b, v9
	v_exp_f32_e32 v4, v4
	v_pk_fma_f32 v[100:101], v[2:3], v[38:39], v[100:101]
	v_add_f32_e32 v0, 1.0, v0
	v_rcp_f32_e32 v2, v0
	v_add_f32_e32 v0, 1.0, v4
	v_rcp_f32_e32 v3, v0
	v_mul_f32_e32 v0, 0xbfb8aa3b, v10
	v_exp_f32_e32 v0, v0
	v_mul_f32_e32 v4, 0xbfb8aa3b, v11
	v_exp_f32_e32 v4, v4
	v_pk_fma_f32 v[98:99], v[2:3], v[40:41], v[98:99]
	v_add_f32_e32 v0, 1.0, v0
	v_rcp_f32_e32 v2, v0
	v_add_f32_e32 v0, 1.0, v4
	v_rcp_f32_e32 v3, v0
	v_mul_f32_e32 v0, 0xbfb8aa3b, v12
	v_exp_f32_e32 v0, v0
	v_mul_f32_e32 v4, 0xbfb8aa3b, v13
	v_exp_f32_e32 v4, v4
	v_pk_fma_f32 v[96:97], v[2:3], v[42:43], v[96:97]
	v_add_f32_e32 v0, 1.0, v0
	v_rcp_f32_e32 v2, v0
	v_add_f32_e32 v0, 1.0, v4
	v_rcp_f32_e32 v3, v0
	v_mul_f32_e32 v0, 0xbfb8aa3b, v14
	v_exp_f32_e32 v0, v0
	v_mul_f32_e32 v4, 0xbfb8aa3b, v15
	v_exp_f32_e32 v4, v4
	v_pk_fma_f32 v[94:95], v[2:3], v[44:45], v[94:95]
	v_add_f32_e32 v0, 1.0, v0
	v_mul_f32_e32 v3, 0xbfb8aa3b, v16
	v_rcp_f32_e32 v2, v0
	v_add_f32_e32 v0, 1.0, v4
	v_exp_f32_e32 v4, v3
	v_mul_f32_e32 v3, 0xbfb8aa3b, v17
	v_exp_f32_e32 v5, v3
	v_rcp_f32_e32 v3, v0
	v_add_f32_e32 v0, 1.0, v4
	v_rcp_f32_e32 v4, v0
	v_add_f32_e32 v0, 1.0, v5
	v_rcp_f32_e32 v5, v0
	v_pk_fma_f32 v[92:93], v[2:3], v[46:47], v[92:93]
	v_pk_fma_f32 v[90:91], v[4:5], v[48:49], v[90:91]
	s_cbranch_scc1 .LBB0_18
; DI unsigned pack2(float a, float b) { hwf2 v = {a, b}; hwbf2 r = __builtin_convertvector(v, hwbf2); return __builtin_bit_cast(unsigned, r); }
; DI float siluf(float x) { return x * __builtin_amdgcn_rcpf(1.f + __expf(-x)); }
; DI void epi_store64(const float* Ct, int cb, const float* rn, int grp, const float* gain, bool silu, const float* bias,
;                     bf16_t* dst, size_t ldd, int dcol0, int m0, int Mmax) {
;     ...
;   float4 gv = make_float4(1.f, 1.f, 1.f, 1.f), bv = make_float4(0.f, 0.f, 0.f, 0.f);
;   if (rn) gv = *(const float4*)(gain + c);
;   if (bias) bv = *(const float4*)(bias + c);
; #pragma unroll
;   for (int q = 0; q < 8; ++q) {
;     const int row = (tid >> 4) + 16 * q;
;     float4 v = *(const float4*)(Ct + row * 132 + cb + c);
;     v.x += bv.x; v.y += bv.y; v.z += bv.z; v.w += bv.w;
;     if (rn) { const float sc = rn[row * 2 + grp]; v.x *= sc * gv.x; v.y *= sc * gv.y; v.z *= sc * gv.z; v.w *= sc * gv.w; }
;     if (silu) { v.x = siluf(v.x); v.y = siluf(v.y); v.z = siluf(v.z); v.w = siluf(v.w); }
;     uint2 o; o.x = pack2(v.x, v.y); o.y = pack2(v.z, v.w);
;     *(uint2*)(dst + (size_t)(m0 + row) * ldd + dcol0 + c) = o;
;   }
; DI void merge_tile(const Params& p, int mt, int nt, char* smem) {
;     ...
;   float* Ct = (float*)smem;
;   acc_to_ct<1>(mac, Ct);
;   epi_store64(Ct, 0, nullptr, 0, nullptr, false, nullptr, p.merged, 1024, n0, m0, T_TOK);
;   __syncthreads();
	v_mov_b32_e32 v0, v230
	v_mov_b32_e32 v2, v230
	v_and_b32_e32 v3, 31, v0
	v_lshrrev_b32_e32 v0, 3, v0
	v_and_b32_e32 v0, 4, v0
	v_lshrrev_b32_e32 v4, 1, v2
	v_and_or_b32 v4, v4, s47, v0
	v_lshlrev_b32_e32 v0, 1, v2
	v_and_b32_e32 v0, 0x80, v0
	v_lshl_or_b32 v0, v3, 2, v0
	v_mad_u64_u32 v[2:3], s[4:5], v4, s79, v[0:1]
	v_add_u32_e32 v0, 0x400, v2
	ds_write2_b32 v0, v118, v119 offset0:8 offset1:140
	v_add_u32_e32 v0, 0x1000, v2
	ds_write2_b32 v0, v116, v117 offset0:32 offset1:164
	v_add_u32_e32 v0, 0x1400, v2
	ds_write2_b32 v0, v114, v115 offset0:40 offset1:172
	v_add_u32_e32 v0, 0x2000, v2
	ds_write2_b32 v0, v112, v113 offset0:64 offset1:196
	v_add_u32_e32 v0, 0x2400, v2
	ds_write2_b32 v0, v110, v111 offset0:72 offset1:204
	v_add_u32_e32 v0, 0x3000, v2
	ds_write2_b32 v0, v108, v109 offset0:96 offset1:228
	v_add_u32_e32 v0, 0x3400, v2
	ds_write2_b32 v0, v106, v107 offset0:104 offset1:236
	v_add_u32_e32 v0, 0x4200, v2
	ds_write2_b32 v0, v104, v105 offset1:132
	v_add_u32_e32 v0, 0x4600, v2
	ds_write2_b32 v0, v102, v103 offset0:8 offset1:140
	v_add_u32_e32 v0, 0x5200, v2
	ds_write2_b32 v0, v100, v101 offset0:32 offset1:164
	v_add_u32_e32 v0, 0x5600, v2
	ds_write2_b32 v0, v98, v99 offset0:40 offset1:172
	v_add_u32_e32 v0, 0x6200, v2
	ds_write2_b32 v0, v96, v97 offset0:64 offset1:196
	v_add_u32_e32 v0, 0x6600, v2
	ds_write2_b32 v0, v94, v95 offset0:72 offset1:204
	v_add_u32_e32 v0, 0x7200, v2
	ds_write2_b32 v0, v92, v93 offset0:96 offset1:228
	v_add_u32_e32 v0, 0x7600, v2
	ds_write2_b32 v0, v90, v91 offset0:104 offset1:236
	v_mov_b32_e32 v0, v230
	ds_write2_b32 v2, v120, v121 offset1:132
	s_waitcnt lgkmcnt(0)
	s_barrier
	s_lshl_b32 s2, s2, 1
	v_lshlrev_b32_e32 v2, 2, v0
	v_ashrrev_i32_e32 v12, 4, v0
	v_and_b32_e32 v6, 60, v2
	v_mul_lo_u32 v0, v12, s79
	v_lshl_add_u32 v14, v6, 2, v0
	ds_read_b128 v[2:5], v14
	v_readlane_b32 s4, v250, 50
	v_lshlrev_b32_e32 v0, 1, v6
	ds_read_b128 v[6:9], v14 offset:8448
	v_readlane_b32 s5, v250, 51
	s_add_u32 s2, s4, s2
	v_add_u32_e32 v12, s1, v12
	s_addc_u32 s3, s5, 0
	s_waitcnt lgkmcnt(1)
	v_pk_add_f32 v[2:3], v[2:3], 0 op_sel_hi:[1,0]
	v_pk_add_f32 v[4:5], v[4:5], 0 op_sel_hi:[1,0]
	v_ashrrev_i32_e32 v13, 31, v12
	v_lshl_add_u64 v[10:11], s[2:3], 0, v[0:1]
	v_cvt_pk_bf16_f32 v2, v2, v3
	v_cvt_pk_bf16_f32 v3, v4, v5
	v_lshlrev_b64 v[4:5], 11, v[12:13]
	v_lshl_add_u64 v[4:5], v[10:11], 0, v[4:5]
	global_store_dwordx2 v[4:5], v[2:3], off
	s_waitcnt lgkmcnt(0)
	v_pk_add_f32 v[2:3], v[6:7], 0 op_sel_hi:[1,0]
	v_pk_add_f32 v[4:5], v[8:9], 0 op_sel_hi:[1,0]
	v_cvt_pk_bf16_f32 v6, v2, v3
	v_cvt_pk_bf16_f32 v7, v4, v5
	ds_read_b128 v[2:5], v14 offset:16896
	v_add_u32_e32 v8, 16, v12
	v_ashrrev_i32_e32 v9, 31, v8
	v_lshlrev_b64 v[8:9], 11, v[8:9]
	v_lshl_add_u64 v[8:9], v[10:11], 0, v[8:9]
	global_store_dwordx2 v[8:9], v[6:7], off
	ds_read_b128 v[6:9], v14 offset:25344
	s_waitcnt lgkmcnt(1)
	v_pk_add_f32 v[2:3], v[2:3], 0 op_sel_hi:[1,0]
	v_pk_add_f32 v[4:5], v[4:5], 0 op_sel_hi:[1,0]
	v_cvt_pk_bf16_f32 v2, v2, v3
	v_cvt_pk_bf16_f32 v3, v4, v5
	v_add_u32_e32 v4, 32, v12
	v_ashrrev_i32_e32 v5, 31, v4
	v_lshlrev_b64 v[4:5], 11, v[4:5]
	v_lshl_add_u64 v[4:5], v[10:11], 0, v[4:5]
	global_store_dwordx2 v[4:5], v[2:3], off
	s_waitcnt lgkmcnt(0)
	v_pk_add_f32 v[2:3], v[6:7], 0 op_sel_hi:[1,0]
	v_pk_add_f32 v[4:5], v[8:9], 0 op_sel_hi:[1,0]
	v_cvt_pk_bf16_f32 v6, v2, v3
	v_cvt_pk_bf16_f32 v7, v4, v5
	ds_read_b128 v[2:5], v14 offset:33792
	v_add_u32_e32 v8, 48, v12
	v_ashrrev_i32_e32 v9, 31, v8
	v_lshlrev_b64 v[8:9], 11, v[8:9]
	v_lshl_add_u64 v[8:9], v[10:11], 0, v[8:9]
	global_store_dwordx2 v[8:9], v[6:7], off
	ds_read_b128 v[6:9], v14 offset:42240
	s_waitcnt lgkmcnt(1)
	v_pk_add_f32 v[2:3], v[2:3], 0 op_sel_hi:[1,0]
	v_pk_add_f32 v[4:5], v[4:5], 0 op_sel_hi:[1,0]
	v_cvt_pk_bf16_f32 v2, v2, v3
	v_cvt_pk_bf16_f32 v3, v4, v5
	v_add_u32_e32 v4, 64, v12
	v_ashrrev_i32_e32 v5, 31, v4
	v_lshlrev_b64 v[4:5], 11, v[4:5]
	v_lshl_add_u64 v[4:5], v[10:11], 0, v[4:5]
	global_store_dwordx2 v[4:5], v[2:3], off
	s_waitcnt lgkmcnt(0)
	v_pk_add_f32 v[2:3], v[6:7], 0 op_sel_hi:[1,0]
	v_pk_add_f32 v[4:5], v[8:9], 0 op_sel_hi:[1,0]
	v_cvt_pk_bf16_f32 v6, v2, v3
	v_cvt_pk_bf16_f32 v7, v4, v5
	ds_read_b128 v[2:5], v14 offset:50688
	v_add_u32_e32 v8, 0x50, v12
	v_ashrrev_i32_e32 v9, 31, v8
	v_lshlrev_b64 v[8:9], 11, v[8:9]
	v_lshl_add_u64 v[8:9], v[10:11], 0, v[8:9]
	global_store_dwordx2 v[8:9], v[6:7], off
	ds_read_b128 v[6:9], v14 offset:59136
	s_waitcnt lgkmcnt(1)
	v_pk_add_f32 v[2:3], v[2:3], 0 op_sel_hi:[1,0]
	v_pk_add_f32 v[4:5], v[4:5], 0 op_sel_hi:[1,0]
	v_cvt_pk_bf16_f32 v2, v2, v3
	v_cvt_pk_bf16_f32 v3, v4, v5
	v_add_u32_e32 v4, 0x60, v12
	v_ashrrev_i32_e32 v5, 31, v4
	v_lshlrev_b64 v[4:5], 11, v[4:5]
	v_lshl_add_u64 v[4:5], v[10:11], 0, v[4:5]
	global_store_dwordx2 v[4:5], v[2:3], off
	s_waitcnt lgkmcnt(0)
	v_pk_add_f32 v[2:3], v[6:7], 0 op_sel_hi:[1,0]
	v_pk_add_f32 v[4:5], v[8:9], 0 op_sel_hi:[1,0]
	v_cvt_pk_bf16_f32 v2, v2, v3
	v_cvt_pk_bf16_f32 v3, v4, v5
	v_add_u32_e32 v4, 0x70, v12
	v_ashrrev_i32_e32 v5, 31, v4
	v_readlane_b32 s1, v250, 60
	v_lshlrev_b64 v[4:5], 11, v[4:5]
	s_add_i32 s0, s0, s1
	v_lshl_add_u64 v[4:5], v[10:11], 0, v[4:5]
	s_cmpk_gt_u32 s0, 0x1ff
	v_readlane_b32 s6, v250, 52
	v_readlane_b32 s7, v250, 53
	global_store_dwordx2 v[4:5], v[2:3], off
	s_barrier
	s_cbranch_scc0 .LBB0_17

; #define G_STORE(ST, S, unused) do { char* d_ = smem + (ST) * STAGE; \
;     *(uint4*)(d_ + alo[0]) = S##a0; *(uint4*)(d_ + alo[1]) = S##a1; *(uint4*)(d_ + alo[2]) = S##a2; *(uint4*)(d_ + alo[3]) = S##a3; \
;     *(uint4*)(d_ + blo[0]) = S##b0; *(uint4*)(d_ + blo[1]) = S##b1; \
;     if (NBCH == 4) { *(uint4*)(d_ + blo[NBCH - 2]) = S##b2; *(uint4*)(d_ + blo[NBCH - 1]) = S##b3; } } while (0)
; template <int NJ, class RowA>
; DI void gemm_main(f32x16 (&acc)[2][NJ], const bf16_t* __restrict__ A, RowA rowA, size_t kstrideA, int m0, int Mmax,
;                   const bf16_t* __restrict__ Bt, size_t ldb, int n0, int nk, char* smem) {
;     ...
;   __syncthreads();
;   G_LOAD(x0, 0, 0);
;   G_LOAD(x1, 0, 1);
;   G_STORE(0, x0, 0);
;   __syncthreads();
; #pragma unroll 1
;   for (int kt = 0; kt < nk; kt += 2) {
;     G_LOAD(x0, 0, (kt + 2 < nk ? kt + 2 : nk - 1));
;     G_COMPUTE(0);
;     G_STORE(1, x1, 0);
;     __syncthreads();
;     G_LOAD(x1, 0, (kt + 3 < nk ? kt + 3 : nk - 1));
;     G_COMPUTE(1);
;     G_STORE(0, x0, 0);
;     __syncthreads();
;   }
.LBB0_1956:
	ds_read_b128 v[166:169], v0
	ds_read_b128 v[170:173], v139 offset:18432
	ds_read_b128 v[174:177], v139 offset:23040
	ds_read_b128 v[178:181], v0 offset:4608
	s_add_i32 s1, s0, 4
	s_min_u32 s1, s1, 15
	s_lshl_b32 s14, s1, 7
	v_lshl_add_u64 v[98:99], v[122:123], 0, s[14:15]
	v_lshl_add_u64 v[102:103], v[124:125], 0, s[14:15]
	v_lshl_add_u64 v[106:107], v[126:127], 0, s[14:15]
	v_lshl_add_u64 v[110:111], v[128:129], 0, s[14:15]
	v_lshl_add_u64 v[114:115], v[130:131], 0, s[14:15]
	v_lshl_add_u64 v[118:119], v[132:133], 0, s[14:15]
	s_add_i32 s0, s0, 2
	v_lshl_add_u64 v[158:159], v[134:135], 0, s[14:15]
	v_lshl_add_u64 v[160:161], v[136:137], 0, s[14:15]
	s_setprio 1
	ds_read_b128 v[182:185], v0 offset:32
	ds_read_b128 v[186:189], v139 offset:18464
	ds_read_b128 v[190:193], v139 offset:23072
	ds_read_b128 v[194:197], v0 offset:4640
	s_waitcnt lgkmcnt(4)
	v_mfma_f32_32x32x16_bf16 v[50:65], v[166:169], v[170:173], v[50:65]
	global_load_dwordx4 v[98:101], v[98:99], off
	v_mfma_f32_32x32x16_bf16 v[34:49], v[166:169], v[174:177], v[34:49]
	global_load_dwordx4 v[102:105], v[102:103], off
	v_mfma_f32_32x32x16_bf16 v[18:33], v[178:181], v[170:173], v[18:33]
	global_load_dwordx4 v[106:109], v[106:107], off
	v_mfma_f32_32x32x16_bf16 v[2:17], v[178:181], v[174:177], v[2:17]
	global_load_dwordx4 v[110:113], v[110:111], off
	ds_read_b128 v[166:169], v0 offset:64
	ds_read_b128 v[170:173], v139 offset:18496
	ds_read_b128 v[174:177], v139 offset:23104
	ds_read_b128 v[178:181], v0 offset:4672
	s_waitcnt lgkmcnt(4)
	v_mfma_f32_32x32x16_bf16 v[50:65], v[182:185], v[186:189], v[50:65]
	global_load_dwordx4 v[114:117], v[114:115], off
	v_mfma_f32_32x32x16_bf16 v[34:49], v[182:185], v[190:193], v[34:49]
	global_load_dwordx4 v[118:121], v[118:119], off
	v_mfma_f32_32x32x16_bf16 v[18:33], v[194:197], v[186:189], v[18:33]
	global_load_dwordx4 v[146:149], v[160:161], off
	v_mfma_f32_32x32x16_bf16 v[2:17], v[194:197], v[190:193], v[2:17]
	global_load_dwordx4 v[150:153], v[158:159], off
	ds_read_b128 v[182:185], v0 offset:96
	ds_read_b128 v[186:189], v139 offset:18528
	ds_read_b128 v[190:193], v139 offset:23136
	ds_read_b128 v[194:197], v0 offset:4704
	s_waitcnt lgkmcnt(4)
	v_mfma_f32_32x32x16_bf16 v[50:65], v[166:169], v[170:173], v[50:65]
	s_waitcnt vmcnt(8)
	ds_write_b128 v138, v[74:77] offset:36864
	v_mfma_f32_32x32x16_bf16 v[34:49], v[166:169], v[174:177], v[34:49]
	ds_write_b128 v140, v[78:81] offset:36864
	v_mfma_f32_32x32x16_bf16 v[18:33], v[178:181], v[170:173], v[18:33]
	ds_write_b128 v142, v[82:85] offset:36864
	v_mfma_f32_32x32x16_bf16 v[2:17], v[178:181], v[174:177], v[2:17]
	ds_write_b128 v144, v[86:89] offset:36864
	s_waitcnt lgkmcnt(4)
	v_mfma_f32_32x32x16_bf16 v[50:65], v[182:185], v[186:189], v[50:65]
	ds_write_b128 v138, v[90:93] offset:55296
	v_mfma_f32_32x32x16_bf16 v[34:49], v[182:185], v[190:193], v[34:49]
	ds_write_b128 v140, v[94:97] offset:55296
	v_mfma_f32_32x32x16_bf16 v[18:33], v[194:197], v[186:189], v[18:33]
	ds_write_b128 v142, v[66:69] offset:55296
	v_mfma_f32_32x32x16_bf16 v[2:17], v[194:197], v[190:193], v[2:17]
	ds_write_b128 v144, v[70:73] offset:55296
	s_setprio 0
	s_min_u32 s1, s0, 12
	s_lshl_b32 s14, s1, 7
	v_lshl_add_u64 v[66:67], v[122:123], 0, s[14:15]
	v_lshl_add_u64 v[68:69], v[124:125], 0, s[14:15]
	v_lshl_add_u64 v[70:71], v[126:127], 0, s[14:15]
	v_lshl_add_u64 v[72:73], v[128:129], 0, s[14:15]
	v_lshl_add_u64 v[90:91], v[130:131], 0, s[14:15]
	v_lshl_add_u64 v[94:95], v[132:133], 0, s[14:15]
	s_waitcnt lgkmcnt(0)
	s_barrier
	ds_read_b128 v[166:169], v0 offset:36864
	ds_read_b128 v[170:173], v139 offset:55296
	ds_read_b128 v[174:177], v139 offset:59904
	ds_read_b128 v[178:181], v0 offset:41472
	v_lshl_add_u64 v[154:155], v[134:135], 0, s[14:15]
	v_lshl_add_u64 v[156:157], v[136:137], 0, s[14:15]
	s_setprio 1
	ds_read_b128 v[182:185], v0 offset:36896
	ds_read_b128 v[186:189], v139 offset:55328
	ds_read_b128 v[190:193], v139 offset:59936
	ds_read_b128 v[194:197], v0 offset:41504
	s_waitcnt lgkmcnt(4)
	v_mfma_f32_32x32x16_bf16 v[50:65], v[166:169], v[170:173], v[50:65]
	global_load_dwordx4 v[74:77], v[66:67], off offset:384
	v_mfma_f32_32x32x16_bf16 v[34:49], v[166:169], v[174:177], v[34:49]
	global_load_dwordx4 v[78:81], v[68:69], off offset:384
	v_mfma_f32_32x32x16_bf16 v[18:33], v[178:181], v[170:173], v[18:33]
	global_load_dwordx4 v[82:85], v[70:71], off offset:384
	v_mfma_f32_32x32x16_bf16 v[2:17], v[178:181], v[174:177], v[2:17]
	global_load_dwordx4 v[86:89], v[72:73], off offset:384
	ds_read_b128 v[166:169], v0 offset:36928
	ds_read_b128 v[170:173], v139 offset:55360
	ds_read_b128 v[174:177], v139 offset:59968
	ds_read_b128 v[178:181], v0 offset:41536
	s_waitcnt lgkmcnt(4)
	v_mfma_f32_32x32x16_bf16 v[50:65], v[182:185], v[186:189], v[50:65]
	global_load_dwordx4 v[90:93], v[90:91], off offset:384
	v_mfma_f32_32x32x16_bf16 v[34:49], v[182:185], v[190:193], v[34:49]
	global_load_dwordx4 v[94:97], v[94:95], off offset:384
	v_mfma_f32_32x32x16_bf16 v[18:33], v[194:197], v[186:189], v[18:33]
	global_load_dwordx4 v[66:69], v[154:155], off offset:384
	v_mfma_f32_32x32x16_bf16 v[2:17], v[194:197], v[190:193], v[2:17]
	global_load_dwordx4 v[70:73], v[156:157], off offset:384
	ds_read_b128 v[182:185], v0 offset:36960
	ds_read_b128 v[186:189], v139 offset:55392
	ds_read_b128 v[190:193], v139 offset:60000
	ds_read_b128 v[194:197], v0 offset:41568
	s_waitcnt lgkmcnt(4)
	v_mfma_f32_32x32x16_bf16 v[50:65], v[166:169], v[170:173], v[50:65]
	s_waitcnt vmcnt(8)
	ds_write_b128 v138, v[98:101]
	v_mfma_f32_32x32x16_bf16 v[34:49], v[166:169], v[174:177], v[34:49]
	ds_write_b128 v140, v[102:105]
	v_mfma_f32_32x32x16_bf16 v[18:33], v[178:181], v[170:173], v[18:33]
	ds_write_b128 v142, v[106:109]
	v_mfma_f32_32x32x16_bf16 v[2:17], v[178:181], v[174:177], v[2:17]
	ds_write_b128 v144, v[110:113]
	s_waitcnt lgkmcnt(4)
	v_mfma_f32_32x32x16_bf16 v[50:65], v[182:185], v[186:189], v[50:65]
	ds_write_b128 v138, v[114:117] offset:18432
	v_mfma_f32_32x32x16_bf16 v[34:49], v[182:185], v[190:193], v[34:49]
	ds_write_b128 v140, v[118:121] offset:18432
	v_mfma_f32_32x32x16_bf16 v[18:33], v[194:197], v[186:189], v[18:33]
	ds_write_b128 v142, v[150:153] offset:18432
	v_mfma_f32_32x32x16_bf16 v[2:17], v[194:197], v[190:193], v[2:17]
	ds_write_b128 v144, v[146:149] offset:18432
	s_setprio 0
	s_cmp_lt_u32 s0, 14
	s_waitcnt lgkmcnt(0)
	s_barrier
; #define TIDX (tid_launder())
; DI void inproj_tile(const Params& p, int l, int mt, int tn, char* smem) {
;     ...
;   if (tn <= 3) {
;     epi_rownorm(Ct, rn, 64);
;     const float* g = tn < 2 ? p.a_q_norm + l * 64 : p.c_q_norm + l * 64;
;     epi_store64(Ct, 0, rn, 0, g, false, nullptr, p.projA, LDA_A, tn * 128, m0, T_TOK);
;     epi_store64(Ct, 64, rn, 1, g, false, nullptr, p.projA, LDA_A, tn * 128 + 64, m0, T_TOK);
;   } else if (tn == 4) {
;     epi_rownorm(Ct, rn, 128);
;     const float* g = p.a_kv_norm + l * 128;
;     epi_store64(Ct, 0, rn, 0, g, false, nullptr, p.projA, LDA_A, 512, m0, T_TOK);
;     epi_store64(Ct, 64, rn, 1, g + 64, false, nullptr, p.projA, LDA_A, 576, m0, T_TOK);
;   } else if (tn <= 8) {
;     epi_store64(Ct, 0, nullptr, 0, nullptr, false, nullptr, p.projA, LDA_A, tn * 128, m0, T_TOK);
;     epi_store64(Ct, 64, nullptr, 0, nullptr, false, nullptr, p.projA, LDA_A, tn * 128 + 64, m0, T_TOK);
;   } else if (tn == 9) {
;     epi_storeKF(Ct, 0, nullptr, 0, nullptr, p.kidxF + ((size_t)b * 64 + s0 / 32) * 2048);
;     epi_store64(Ct, 64, nullptr, 0, nullptr, false, nullptr, p.projA, LDA_A, tn * 128 + 64, m0, T_TOK);
;   } else if (tn == 10) {
;     epi_rownorm(Ct, rn, 64);
;     epi_store64(Ct, 0, nullptr, 0, nullptr, false, nullptr, p.projA, LDA_A, 1280, m0, T_TOK);
;     epi_storeKF(Ct, 64, rn, 1, p.c_k_norm + (l * 3 + 1) * 64, p.kselF + ((size_t)b * 64 + s0 / 32) * 2048);
;   } else if (tn == 11) {
;     epi_rownorm(Ct, rn, 64);
;     epi_storeKF(Ct, 0, rn, 0, p.c_k_norm + (l * 3 + 2) * 64, p.kwinF + ((size_t)b * 64 + s0 / 32) * 2048);
;     epi_storeVF(Ct, 64, p.vselT + ((size_t)b * 64 + s0 / 32) * 2048);
;   } else if (tn == 12) {
;     epi_storeVF(Ct, 0, p.vwinT + ((size_t)b * 64 + s0 / 32) * 2048);
;     for (int idx = TIDX; idx < 128 * 32; idx += 256) {
;       const int row = idx >> 5, c = idx & 31;
;       p.small[(size_t)(m0 + row) * 32 + c] = Ct[row * 132 + 64 + c];
;     }
;   } else if (tn <= 24) {
;     const int c0 = (tn - 13) * 128;
;     epi_store64(Ct, 0, nullptr, 0, nullptr, false, nullptr, p.projB, LDA_B, c0, m0, T_TOK);
;     epi_store64(Ct, 64, nullptr, 0, nullptr, false, nullptr, p.projB, LDA_B, c0 + 64, m0, T_TOK);
;   } else {
;     const int c0 = (tn - 25) * 128;
;     epi_store64(Ct, 0, nullptr, 0, nullptr, true, nullptr, p.projZ, LDA_Z, c0, m0, T_TOK);
	s_cbranch_scc1 .LBB0_1956
	v_mov_b32_e32 v0, v230
	s_waitcnt vmcnt(1)
	v_mov_b32_e32 v66, v230
	v_and_b32_e32 v67, 31, v0
	v_lshrrev_b32_e32 v0, 3, v0
	v_and_b32_e32 v0, 4, v0
	v_lshrrev_b32_e32 v68, 1, v66
	v_and_or_b32 v0, v68, s47, v0
	v_and_or_b32 v66, v66, 64, v67
	v_mul_lo_u32 v0, v0, s79
	v_lshl_add_u32 v0, v66, 2, v0
	ds_write2_b32 v0, v50, v34 offset1:32
	ds_write2_b32 v0, v51, v35 offset0:132 offset1:164
	v_add_u32_e32 v34, 0x400, v0
	ds_write2_b32 v34, v52, v36 offset0:8 offset1:40
	ds_write2_b32 v34, v53, v37 offset0:140 offset1:172
	v_add_u32_e32 v34, 0x1000, v0
	ds_write2_b32 v34, v54, v38 offset0:32 offset1:64
	ds_write2_b32 v34, v55, v39 offset0:164 offset1:196
	v_add_u32_e32 v34, 0x1400, v0
	ds_write2_b32 v34, v56, v40 offset0:40 offset1:72
	ds_write2_b32 v34, v57, v41 offset0:172 offset1:204
	v_add_u32_e32 v34, 0x2000, v0
	ds_write2_b32 v34, v58, v42 offset0:64 offset1:96
	ds_write2_b32 v34, v59, v43 offset0:196 offset1:228
	v_add_u32_e32 v34, 0x2400, v0
	ds_write2_b32 v34, v60, v44 offset0:72 offset1:104
	ds_write2_b32 v34, v61, v45 offset0:204 offset1:236
	v_add_u32_e32 v34, 0x3000, v0
	ds_write2_b32 v34, v62, v46 offset0:96 offset1:128
	v_add_u32_e32 v34, 0x3200, v0
	ds_write2_b32 v34, v63, v47 offset0:100 offset1:132
	v_add_u32_e32 v34, 0x3400, v0
	ds_write2_b32 v34, v64, v48 offset0:104 offset1:136
	v_add_u32_e32 v34, 0x3600, v0
	ds_write2_b32 v34, v65, v49 offset0:108 offset1:140
	v_add_u32_e32 v34, 0x4000, v0
	ds_write2_b32 v34, v18, v2 offset0:128 offset1:160
	v_add_u32_e32 v2, 0x4400, v0
	ds_write2_b32 v2, v19, v3 offset0:4 offset1:36
	ds_write2_b32 v2, v20, v4 offset0:136 offset1:168
	v_add_u32_e32 v2, 0x4800, v0
	ds_write2_b32 v2, v21, v5 offset0:12 offset1:44
	v_add_u32_e32 v2, 0x5000, v0
	ds_write2_b32 v2, v22, v6 offset0:160 offset1:192
	v_add_u32_e32 v2, 0x5400, v0
	ds_write2_b32 v2, v23, v7 offset0:36 offset1:68
	ds_write2_b32 v2, v24, v8 offset0:168 offset1:200
	v_add_u32_e32 v2, 0x5800, v0
	ds_write2_b32 v2, v25, v9 offset0:44 offset1:76
	v_add_u32_e32 v2, 0x6000, v0
	ds_write2_b32 v2, v26, v10 offset0:192 offset1:224
	v_add_u32_e32 v2, 0x6400, v0
	ds_write2_b32 v2, v27, v11 offset0:68 offset1:100
	ds_write2_b32 v2, v28, v12 offset0:200 offset1:232
	v_add_u32_e32 v2, 0x6800, v0
	ds_write2_b32 v2, v29, v13 offset0:76 offset1:108
	v_add_u32_e32 v2, 0x7200, v0
	ds_write2_b32 v2, v30, v14 offset0:96 offset1:128
	v_add_u32_e32 v2, 0x7400, v0
	ds_write2_b32 v2, v31, v15 offset0:100 offset1:132
	v_add_u32_e32 v2, 0x7600, v0
	v_add_u32_e32 v0, 0x7800, v0
	s_cmp_gt_i32 s12, 3
	s_mov_b64 s[0:1], -1
	ds_write2_b32 v2, v32, v16 offset0:104 offset1:136
	ds_write2_b32 v0, v33, v17 offset0:108 offset1:140
	s_waitcnt lgkmcnt(0)
	s_barrier
	s_cbranch_scc0 .LBB0_2086
	s_cmp_lg_u32 s12, 4
	s_cbranch_scc0 .LBB0_2045
	s_cmp_gt_u32 s12, 8
	s_cbranch_scc0 .LBB0_2042
	s_ashr_i32 s0, s3, 7
	s_add_i32 s4, s0, s4
	s_ashr_i32 s0, s11, 31
	s_lshr_b32 s0, s0, 21
	s_add_i32 s0, s11, s0
	s_and_b32 s0, s0, 0xfffff800
	s_sub_i32 s13, s11, s0
	s_cmp_lt_i32 s12, 11
	s_mov_b64 s[0:1], -1
	s_cbranch_scc1 .LBB0_2012
	s_cmp_lt_i32 s12, 12
	s_cbranch_scc1 .LBB0_1982
	s_cmp_lg_u32 s12, 12
	s_cbranch_scc0 .LBB0_1968
	s_cmp_gt_u32 s12, 24
	s_mov_b32 s3, s15
	s_cbranch_scc0 .LBB0_1965
	v_mov_b32_e32 v0, v230
	v_readlane_b32 s16, v252, 57
	s_lshl_b64 s[0:1], s[2:3], 1
	v_lshlrev_b32_e32 v2, 2, v0
	v_readlane_b32 s28, v253, 5
	v_and_b32_e32 v4, 60, v2
	v_readlane_b32 s29, v253, 6
	s_add_u32 s0, s28, s0
	v_ashrrev_i32_e32 v10, 4, v0
	s_addc_u32 s1, s29, s1
	v_lshlrev_b32_e32 v0, 1, v4
	v_lshl_add_u64 v[2:3], s[0:1], 0, v[0:1]
	v_mul_lo_u32 v0, v10, s79
	v_lshl_add_u32 v0, v4, 2, v0
	ds_read_b128 v[4:7], v0
	s_movk_i32 s6, 0xe700
	s_mov_b32 s7, -1
	v_lshl_add_u64 v[2:3], v[2:3], 0, s[6:7]
	v_readlane_b32 s17, v252, 58
	s_waitcnt lgkmcnt(0)
	v_pk_add_f32 v[4:5], v[4:5], 0 op_sel_hi:[1,0]
	v_pk_add_f32 v[6:7], v[6:7], 0 op_sel_hi:[1,0]
	v_mul_f32_e32 v8, 0xbfb8aa3b, v4
	v_mul_f32_e32 v9, 0xbfb8aa3b, v5
	v_exp_f32_e32 v8, v8
	v_exp_f32_e32 v9, v9
	v_readlane_b32 s18, v252, 59
	v_readlane_b32 s19, v252, 60
	v_add_f32_e32 v8, 1.0, v8
	v_add_f32_e32 v9, 1.0, v9
	v_rcp_f32_e32 v8, v8
	v_rcp_f32_e32 v9, v9
	v_readlane_b32 s20, v252, 61
	v_readlane_b32 s21, v252, 62
	v_readlane_b32 s22, v252, 63
	v_pk_mul_f32 v[4:5], v[4:5], v[8:9]
	v_mul_f32_e32 v8, 0xbfb8aa3b, v6
	v_mul_f32_e32 v9, 0xbfb8aa3b, v7
	v_exp_f32_e32 v8, v8
	v_exp_f32_e32 v9, v9
	v_readlane_b32 s23, v253, 0
	v_readlane_b32 s24, v253, 1
	v_add_f32_e32 v8, 1.0, v8
	v_add_f32_e32 v9, 1.0, v9
	v_rcp_f32_e32 v8, v8
	v_rcp_f32_e32 v9, v9
	v_readlane_b32 s25, v253, 2
	v_readlane_b32 s26, v253, 3
	v_readlane_b32 s27, v253, 4
	v_pk_mul_f32 v[6:7], v[6:7], v[8:9]
	v_cvt_pk_bf16_f32 v8, v4, v5
	v_add_u32_e32 v4, s11, v10
	v_ashrrev_i32_e32 v5, 31, v4
	v_cvt_pk_bf16_f32 v9, v6, v7
	v_lshlrev_b64 v[6:7], 11, v[4:5]
	v_lshl_add_u64 v[6:7], v[2:3], 0, v[6:7]
	global_store_dwordx2 v[6:7], v[8:9], off
	ds_read_b128 v[6:9], v0 offset:8448
	v_readlane_b32 s30, v253, 7
	v_readlane_b32 s31, v253, 8
	s_waitcnt lgkmcnt(0)
	v_pk_add_f32 v[6:7], v[6:7], 0 op_sel_hi:[1,0]
	s_nop 0
	v_mul_f32_e32 v5, 0xbfb8aa3b, v6
	v_exp_f32_e32 v5, v5
	v_pk_add_f32 v[8:9], v[8:9], 0 op_sel_hi:[1,0]
	v_add_f32_e32 v5, 1.0, v5
	v_rcp_f32_e32 v10, v5
	v_mul_f32_e32 v5, 0xbfb8aa3b, v7
	v_exp_f32_e32 v5, v5
	s_nop 0
	v_add_f32_e32 v5, 1.0, v5
	v_rcp_f32_e32 v11, v5
	v_mul_f32_e32 v5, 0xbfb8aa3b, v8
	v_exp_f32_e32 v5, v5
	v_pk_mul_f32 v[6:7], v[6:7], v[10:11]
	s_nop 0
	v_cvt_pk_bf16_f32 v6, v6, v7
	v_add_f32_e32 v5, 1.0, v5
	v_rcp_f32_e32 v10, v5
	v_mul_f32_e32 v5, 0xbfb8aa3b, v9
	v_exp_f32_e32 v5, v5
	s_nop 0
	v_add_f32_e32 v5, 1.0, v5
	v_rcp_f32_e32 v11, v5
	s_nop 0
	v_pk_mul_f32 v[8:9], v[8:9], v[10:11]
	s_nop 0
	v_cvt_pk_bf16_f32 v7, v8, v9
	v_add_u32_e32 v8, 16, v4
	v_ashrrev_i32_e32 v9, 31, v8
	v_lshlrev_b64 v[8:9], 11, v[8:9]
	v_lshl_add_u64 v[8:9], v[2:3], 0, v[8:9]
	global_store_dwordx2 v[8:9], v[6:7], off
	ds_read_b128 v[6:9], v0 offset:16896
	s_waitcnt lgkmcnt(0)
; DI unsigned pack2(float a, float b) { hwf2 v = {a, b}; hwbf2 r = __builtin_convertvector(v, hwbf2); return __builtin_bit_cast(unsigned, r); }
; DI float siluf(float x) { return x * __builtin_amdgcn_rcpf(1.f + __expf(-x)); }
; DI void epi_store64(const float* Ct, int cb, const float* rn, int grp, const float* gain, bool silu, const float* bias,
;                     bf16_t* dst, size_t ldd, int dcol0, int m0, int Mmax) {
;     ...
;   for (int q = 0; q < 8; ++q) {
;     const int row = (tid >> 4) + 16 * q;
;     float4 v = *(const float4*)(Ct + row * 132 + cb + c);
;     v.x += bv.x; v.y += bv.y; v.z += bv.z; v.w += bv.w;
;     if (rn) { const float sc = rn[row * 2 + grp]; v.x *= sc * gv.x; v.y *= sc * gv.y; v.z *= sc * gv.z; v.w *= sc * gv.w; }
;     if (silu) { v.x = siluf(v.x); v.y = siluf(v.y); v.z = siluf(v.z); v.w = siluf(v.w); }
;     uint2 o; o.x = pack2(v.x, v.y); o.y = pack2(v.z, v.w);
;     *(uint2*)(dst + (size_t)(m0 + row) * ldd + dcol0 + c) = o;
;   }
; DI void inproj_tile(const Params& p, int l, int mt, int tn, char* smem) {
;     ...
;     epi_store64(Ct, 64, nullptr, 0, nullptr, true, nullptr, p.projZ, LDA_Z, c0 + 64, m0, T_TOK);
	v_pk_add_f32 v[6:7], v[6:7], 0 op_sel_hi:[1,0]
	s_nop 0
	v_mul_f32_e32 v5, 0xbfb8aa3b, v6
	v_exp_f32_e32 v5, v5
	v_pk_add_f32 v[8:9], v[8:9], 0 op_sel_hi:[1,0]
	v_add_f32_e32 v5, 1.0, v5
	v_rcp_f32_e32 v10, v5
	v_mul_f32_e32 v5, 0xbfb8aa3b, v7
	v_exp_f32_e32 v5, v5
	s_nop 0
	v_add_f32_e32 v5, 1.0, v5
	v_rcp_f32_e32 v11, v5
	v_mul_f32_e32 v5, 0xbfb8aa3b, v8
	v_exp_f32_e32 v5, v5
	v_pk_mul_f32 v[6:7], v[6:7], v[10:11]
	s_nop 0
	v_cvt_pk_bf16_f32 v6, v6, v7
	v_add_f32_e32 v5, 1.0, v5
	v_rcp_f32_e32 v10, v5
	v_mul_f32_e32 v5, 0xbfb8aa3b, v9
	v_exp_f32_e32 v5, v5
	s_nop 0
	v_add_f32_e32 v5, 1.0, v5
	v_rcp_f32_e32 v11, v5
	s_nop 0
	v_pk_mul_f32 v[8:9], v[8:9], v[10:11]
	s_nop 0
	v_cvt_pk_bf16_f32 v7, v8, v9
	v_add_u32_e32 v8, 32, v4
	v_ashrrev_i32_e32 v9, 31, v8
	v_lshlrev_b64 v[8:9], 11, v[8:9]
	v_lshl_add_u64 v[8:9], v[2:3], 0, v[8:9]
	global_store_dwordx2 v[8:9], v[6:7], off
	ds_read_b128 v[6:9], v0 offset:25344
	s_waitcnt lgkmcnt(0)
	v_pk_add_f32 v[6:7], v[6:7], 0 op_sel_hi:[1,0]
	s_nop 0
	v_mul_f32_e32 v5, 0xbfb8aa3b, v6
	v_exp_f32_e32 v5, v5
	v_pk_add_f32 v[8:9], v[8:9], 0 op_sel_hi:[1,0]
	v_add_f32_e32 v5, 1.0, v5
	v_rcp_f32_e32 v10, v5
	v_mul_f32_e32 v5, 0xbfb8aa3b, v7
	v_exp_f32_e32 v5, v5
	s_nop 0
	v_add_f32_e32 v5, 1.0, v5
	v_rcp_f32_e32 v11, v5
	v_mul_f32_e32 v5, 0xbfb8aa3b, v8
	v_exp_f32_e32 v5, v5
	v_pk_mul_f32 v[6:7], v[6:7], v[10:11]
	s_nop 0
	v_cvt_pk_bf16_f32 v6, v6, v7
	v_add_f32_e32 v5, 1.0, v5
	v_rcp_f32_e32 v10, v5
	v_mul_f32_e32 v5, 0xbfb8aa3b, v9
	v_exp_f32_e32 v5, v5
	s_nop 0
	v_add_f32_e32 v5, 1.0, v5
	v_rcp_f32_e32 v11, v5
	s_nop 0
	v_pk_mul_f32 v[8:9], v[8:9], v[10:11]
	s_nop 0
	v_cvt_pk_bf16_f32 v7, v8, v9
	v_add_u32_e32 v8, 48, v4
	v_ashrrev_i32_e32 v9, 31, v8
	v_lshlrev_b64 v[8:9], 11, v[8:9]
	v_lshl_add_u64 v[8:9], v[2:3], 0, v[8:9]
	global_store_dwordx2 v[8:9], v[6:7], off
	ds_read_b128 v[6:9], v0 offset:33792
	s_waitcnt lgkmcnt(0)
	v_pk_add_f32 v[6:7], v[6:7], 0 op_sel_hi:[1,0]
	s_nop 0
	v_mul_f32_e32 v5, 0xbfb8aa3b, v6
	v_exp_f32_e32 v5, v5
	v_pk_add_f32 v[8:9], v[8:9], 0 op_sel_hi:[1,0]
	v_add_f32_e32 v5, 1.0, v5
	v_rcp_f32_e32 v10, v5
	v_mul_f32_e32 v5, 0xbfb8aa3b, v7
	v_exp_f32_e32 v5, v5
	s_nop 0
	v_add_f32_e32 v5, 1.0, v5
	v_rcp_f32_e32 v11, v5
	v_mul_f32_e32 v5, 0xbfb8aa3b, v8
	v_exp_f32_e32 v5, v5
	v_pk_mul_f32 v[6:7], v[6:7], v[10:11]
	s_nop 0
	v_cvt_pk_bf16_f32 v6, v6, v7
	v_add_f32_e32 v5, 1.0, v5
	v_rcp_f32_e32 v10, v5
	v_mul_f32_e32 v5, 0xbfb8aa3b, v9
	v_exp_f32_e32 v5, v5
	s_nop 0
	v_add_f32_e32 v5, 1.0, v5
	v_rcp_f32_e32 v11, v5
	s_nop 0
	v_pk_mul_f32 v[8:9], v[8:9], v[10:11]
	s_nop 0
	v_cvt_pk_bf16_f32 v7, v8, v9
	v_add_u32_e32 v8, 64, v4
	v_ashrrev_i32_e32 v9, 31, v8
	v_lshlrev_b64 v[8:9], 11, v[8:9]
	v_lshl_add_u64 v[8:9], v[2:3], 0, v[8:9]
	global_store_dwordx2 v[8:9], v[6:7], off
	ds_read_b128 v[6:9], v0 offset:42240
	s_waitcnt lgkmcnt(0)
	v_pk_add_f32 v[6:7], v[6:7], 0 op_sel_hi:[1,0]
	s_nop 0
	v_mul_f32_e32 v5, 0xbfb8aa3b, v6
	v_exp_f32_e32 v5, v5
	v_pk_add_f32 v[8:9], v[8:9], 0 op_sel_hi:[1,0]
	v_add_f32_e32 v5, 1.0, v5
	v_rcp_f32_e32 v10, v5
	v_mul_f32_e32 v5, 0xbfb8aa3b, v7
	v_exp_f32_e32 v5, v5
	s_nop 0
	v_add_f32_e32 v5, 1.0, v5
	v_rcp_f32_e32 v11, v5
	v_mul_f32_e32 v5, 0xbfb8aa3b, v8
	v_exp_f32_e32 v5, v5
	v_pk_mul_f32 v[6:7], v[6:7], v[10:11]
	s_nop 0
	v_cvt_pk_bf16_f32 v6, v6, v7
	v_add_f32_e32 v5, 1.0, v5
	v_rcp_f32_e32 v10, v5
	v_mul_f32_e32 v5, 0xbfb8aa3b, v9
	v_exp_f32_e32 v5, v5
	s_nop 0
	v_add_f32_e32 v5, 1.0, v5
	v_rcp_f32_e32 v11, v5
	s_nop 0
	v_pk_mul_f32 v[8:9], v[8:9], v[10:11]
	s_nop 0
	v_cvt_pk_bf16_f32 v7, v8, v9
	v_add_u32_e32 v8, 0x50, v4
	v_ashrrev_i32_e32 v9, 31, v8
	v_lshlrev_b64 v[8:9], 11, v[8:9]
	v_lshl_add_u64 v[8:9], v[2:3], 0, v[8:9]
	global_store_dwordx2 v[8:9], v[6:7], off
	ds_read_b128 v[6:9], v0 offset:50688
	s_waitcnt lgkmcnt(0)
	v_pk_add_f32 v[6:7], v[6:7], 0 op_sel_hi:[1,0]
	s_nop 0
	v_mul_f32_e32 v5, 0xbfb8aa3b, v6
	v_exp_f32_e32 v5, v5
	v_pk_add_f32 v[8:9], v[8:9], 0 op_sel_hi:[1,0]
	v_add_f32_e32 v5, 1.0, v5
	v_rcp_f32_e32 v10, v5
	v_mul_f32_e32 v5, 0xbfb8aa3b, v7
	v_exp_f32_e32 v5, v5
	s_nop 0
	v_add_f32_e32 v5, 1.0, v5
	v_rcp_f32_e32 v11, v5
	v_mul_f32_e32 v5, 0xbfb8aa3b, v8
	v_exp_f32_e32 v5, v5
	v_pk_mul_f32 v[6:7], v[6:7], v[10:11]
	s_nop 0
	v_cvt_pk_bf16_f32 v6, v6, v7
	v_add_f32_e32 v5, 1.0, v5
	v_rcp_f32_e32 v10, v5
	v_mul_f32_e32 v5, 0xbfb8aa3b, v9
	v_exp_f32_e32 v5, v5
	s_nop 0
	v_add_f32_e32 v5, 1.0, v5
	v_rcp_f32_e32 v11, v5
	s_nop 0
	v_pk_mul_f32 v[8:9], v[8:9], v[10:11]
	s_nop 0
	v_cvt_pk_bf16_f32 v7, v8, v9
	v_add_u32_e32 v8, 0x60, v4
	v_ashrrev_i32_e32 v9, 31, v8
	v_lshlrev_b64 v[8:9], 11, v[8:9]
	v_lshl_add_u64 v[8:9], v[2:3], 0, v[8:9]
	global_store_dwordx2 v[8:9], v[6:7], off
	ds_read_b128 v[6:9], v0 offset:59136
	v_add_u32_e32 v4, 0x70, v4
	v_ashrrev_i32_e32 v5, 31, v4
	v_lshlrev_b64 v[4:5], 11, v[4:5]
	v_lshl_add_u64 v[2:3], v[2:3], 0, v[4:5]
	s_waitcnt lgkmcnt(0)
	v_pk_add_f32 v[6:7], v[6:7], 0 op_sel_hi:[1,0]
	v_pk_add_f32 v[8:9], v[8:9], 0 op_sel_hi:[1,0]
	v_mul_f32_e32 v0, 0xbfb8aa3b, v6
	v_exp_f32_e32 v0, v0
	s_nop 0
	v_add_f32_e32 v0, 1.0, v0
	v_rcp_f32_e32 v10, v0
	v_mul_f32_e32 v0, 0xbfb8aa3b, v7
	v_exp_f32_e32 v0, v0
	s_nop 0
	v_add_f32_e32 v0, 1.0, v0
	v_rcp_f32_e32 v11, v0
	v_mul_f32_e32 v0, 0xbfb8aa3b, v8
	v_exp_f32_e32 v0, v0
	v_pk_mul_f32 v[6:7], v[6:7], v[10:11]
	s_nop 0
	v_cvt_pk_bf16_f32 v6, v6, v7
	v_add_f32_e32 v0, 1.0, v0
	v_rcp_f32_e32 v10, v0
	v_mul_f32_e32 v0, 0xbfb8aa3b, v9
	v_exp_f32_e32 v0, v0
	s_nop 0
	v_add_f32_e32 v0, 1.0, v0
	v_rcp_f32_e32 v11, v0
	v_mov_b32_e32 v0, v230
	v_pk_mul_f32 v[8:9], v[8:9], v[10:11]
	s_nop 0
	v_cvt_pk_bf16_f32 v7, v8, v9
	global_store_dwordx2 v[2:3], v[6:7], off
	s_nop 0
	v_lshlrev_b32_e32 v2, 2, v0
	v_and_b32_e32 v4, 60, v2
	v_ashrrev_i32_e32 v10, 4, v0
	v_lshlrev_b32_e32 v0, 1, v4
	v_lshl_add_u64 v[2:3], s[0:1], 0, v[0:1]
	v_mul_lo_u32 v0, v10, s79
	v_lshl_add_u32 v0, v4, 2, v0
	ds_read_b128 v[4:7], v0 offset:256
	s_movk_i32 s0, 0xe780
	s_mov_b32 s1, -1
	v_lshl_add_u64 v[2:3], v[2:3], 0, s[0:1]
	s_mov_b64 s[0:1], 0
	s_waitcnt lgkmcnt(0)
; DI unsigned pack2(float a, float b) { hwf2 v = {a, b}; hwbf2 r = __builtin_convertvector(v, hwbf2); return __builtin_bit_cast(unsigned, r); }
; DI float siluf(float x) { return x * __builtin_amdgcn_rcpf(1.f + __expf(-x)); }
; DI void epi_store64(const float* Ct, int cb, const float* rn, int grp, const float* gain, bool silu, const float* bias,
;                     bf16_t* dst, size_t ldd, int dcol0, int m0, int Mmax) {
;     ...
;   for (int q = 0; q < 8; ++q) {
;     const int row = (tid >> 4) + 16 * q;
;     float4 v = *(const float4*)(Ct + row * 132 + cb + c);
;     v.x += bv.x; v.y += bv.y; v.z += bv.z; v.w += bv.w;
;     if (rn) { const float sc = rn[row * 2 + grp]; v.x *= sc * gv.x; v.y *= sc * gv.y; v.z *= sc * gv.z; v.w *= sc * gv.w; }
;     if (silu) { v.x = siluf(v.x); v.y = siluf(v.y); v.z = siluf(v.z); v.w = siluf(v.w); }
;     uint2 o; o.x = pack2(v.x, v.y); o.y = pack2(v.z, v.w);
;     *(uint2*)(dst + (size_t)(m0 + row) * ldd + dcol0 + c) = o;
;   }
; DI void inproj_tile(const Params& p, int l, int mt, int tn, char* smem) {
;     ...
;     epi_store64(Ct, 64, nullptr, 0, nullptr, true, nullptr, p.projZ, LDA_Z, c0 + 64, m0, T_TOK);
	v_pk_add_f32 v[4:5], v[4:5], 0 op_sel_hi:[1,0]
	v_pk_add_f32 v[6:7], v[6:7], 0 op_sel_hi:[1,0]
	v_mul_f32_e32 v8, 0xbfb8aa3b, v4
	v_mul_f32_e32 v9, 0xbfb8aa3b, v5
	v_exp_f32_e32 v8, v8
	v_exp_f32_e32 v9, v9
	v_add_f32_e32 v8, 1.0, v8
	v_add_f32_e32 v9, 1.0, v9
	v_rcp_f32_e32 v8, v8
	v_rcp_f32_e32 v9, v9
	s_nop 0
	v_pk_mul_f32 v[4:5], v[4:5], v[8:9]
	v_mul_f32_e32 v8, 0xbfb8aa3b, v6
	v_mul_f32_e32 v9, 0xbfb8aa3b, v7
	v_exp_f32_e32 v8, v8
	v_exp_f32_e32 v9, v9
	v_add_f32_e32 v8, 1.0, v8
	v_add_f32_e32 v9, 1.0, v9
	v_rcp_f32_e32 v8, v8
	v_rcp_f32_e32 v9, v9
	s_nop 0
	v_pk_mul_f32 v[6:7], v[6:7], v[8:9]
	v_cvt_pk_bf16_f32 v8, v4, v5
	v_add_u32_e32 v4, s11, v10
	v_ashrrev_i32_e32 v5, 31, v4
	v_cvt_pk_bf16_f32 v9, v6, v7
	v_lshlrev_b64 v[6:7], 11, v[4:5]
	v_lshl_add_u64 v[6:7], v[2:3], 0, v[6:7]
	global_store_dwordx2 v[6:7], v[8:9], off
	ds_read_b128 v[6:9], v0 offset:8704
	s_waitcnt lgkmcnt(0)
	v_pk_add_f32 v[6:7], v[6:7], 0 op_sel_hi:[1,0]
	s_nop 0
	v_mul_f32_e32 v5, 0xbfb8aa3b, v6
	v_exp_f32_e32 v5, v5
	v_pk_add_f32 v[8:9], v[8:9], 0 op_sel_hi:[1,0]
	v_add_f32_e32 v5, 1.0, v5
	v_rcp_f32_e32 v10, v5
	v_mul_f32_e32 v5, 0xbfb8aa3b, v7
	v_exp_f32_e32 v5, v5
	s_nop 0
	v_add_f32_e32 v5, 1.0, v5
	v_rcp_f32_e32 v11, v5
	v_mul_f32_e32 v5, 0xbfb8aa3b, v8
	v_exp_f32_e32 v5, v5
	v_pk_mul_f32 v[6:7], v[6:7], v[10:11]
	s_nop 0
	v_cvt_pk_bf16_f32 v6, v6, v7
	v_add_f32_e32 v5, 1.0, v5
	v_rcp_f32_e32 v10, v5
	v_mul_f32_e32 v5, 0xbfb8aa3b, v9
	v_exp_f32_e32 v5, v5
	s_nop 0
	v_add_f32_e32 v5, 1.0, v5
	v_rcp_f32_e32 v11, v5
	s_nop 0
	v_pk_mul_f32 v[8:9], v[8:9], v[10:11]
	s_nop 0
	v_cvt_pk_bf16_f32 v7, v8, v9
	v_add_u32_e32 v8, 16, v4
	v_ashrrev_i32_e32 v9, 31, v8
	v_lshlrev_b64 v[8:9], 11, v[8:9]
	v_lshl_add_u64 v[8:9], v[2:3], 0, v[8:9]
	global_store_dwordx2 v[8:9], v[6:7], off
	ds_read_b128 v[6:9], v0 offset:17152
	s_waitcnt lgkmcnt(0)
	v_pk_add_f32 v[6:7], v[6:7], 0 op_sel_hi:[1,0]
	s_nop 0
	v_mul_f32_e32 v5, 0xbfb8aa3b, v6
	v_exp_f32_e32 v5, v5
	v_pk_add_f32 v[8:9], v[8:9], 0 op_sel_hi:[1,0]
	v_add_f32_e32 v5, 1.0, v5
	v_rcp_f32_e32 v10, v5
	v_mul_f32_e32 v5, 0xbfb8aa3b, v7
	v_exp_f32_e32 v5, v5
	s_nop 0
	v_add_f32_e32 v5, 1.0, v5
	v_rcp_f32_e32 v11, v5
	v_mul_f32_e32 v5, 0xbfb8aa3b, v8
	v_exp_f32_e32 v5, v5
	v_pk_mul_f32 v[6:7], v[6:7], v[10:11]
	s_nop 0
	v_cvt_pk_bf16_f32 v6, v6, v7
	v_add_f32_e32 v5, 1.0, v5
	v_rcp_f32_e32 v10, v5
	v_mul_f32_e32 v5, 0xbfb8aa3b, v9
	v_exp_f32_e32 v5, v5
	s_nop 0
	v_add_f32_e32 v5, 1.0, v5
	v_rcp_f32_e32 v11, v5
	s_nop 0
	v_pk_mul_f32 v[8:9], v[8:9], v[10:11]
	s_nop 0
	v_cvt_pk_bf16_f32 v7, v8, v9
	v_add_u32_e32 v8, 32, v4
	v_ashrrev_i32_e32 v9, 31, v8
	v_lshlrev_b64 v[8:9], 11, v[8:9]
	v_lshl_add_u64 v[8:9], v[2:3], 0, v[8:9]
	global_store_dwordx2 v[8:9], v[6:7], off
	ds_read_b128 v[6:9], v0 offset:25600
	s_waitcnt lgkmcnt(0)
	v_pk_add_f32 v[6:7], v[6:7], 0 op_sel_hi:[1,0]
	s_nop 0
	v_mul_f32_e32 v5, 0xbfb8aa3b, v6
	v_exp_f32_e32 v5, v5
	v_pk_add_f32 v[8:9], v[8:9], 0 op_sel_hi:[1,0]
	v_add_f32_e32 v5, 1.0, v5
	v_rcp_f32_e32 v10, v5
	v_mul_f32_e32 v5, 0xbfb8aa3b, v7
	v_exp_f32_e32 v5, v5
	s_nop 0
	v_add_f32_e32 v5, 1.0, v5
	v_rcp_f32_e32 v11, v5
	v_mul_f32_e32 v5, 0xbfb8aa3b, v8
	v_exp_f32_e32 v5, v5
	v_pk_mul_f32 v[6:7], v[6:7], v[10:11]
	s_nop 0
	v_cvt_pk_bf16_f32 v6, v6, v7
	v_add_f32_e32 v5, 1.0, v5
	v_rcp_f32_e32 v10, v5
	v_mul_f32_e32 v5, 0xbfb8aa3b, v9
	v_exp_f32_e32 v5, v5
	s_nop 0
	v_add_f32_e32 v5, 1.0, v5
	v_rcp_f32_e32 v11, v5
	s_nop 0
	v_pk_mul_f32 v[8:9], v[8:9], v[10:11]
	s_nop 0
	v_cvt_pk_bf16_f32 v7, v8, v9
	v_add_u32_e32 v8, 48, v4
	v_ashrrev_i32_e32 v9, 31, v8
	v_lshlrev_b64 v[8:9], 11, v[8:9]
	v_lshl_add_u64 v[8:9], v[2:3], 0, v[8:9]
	global_store_dwordx2 v[8:9], v[6:7], off
	ds_read_b128 v[6:9], v0 offset:34048
	s_waitcnt lgkmcnt(0)
; DI unsigned pack2(float a, float b) { hwf2 v = {a, b}; hwbf2 r = __builtin_convertvector(v, hwbf2); return __builtin_bit_cast(unsigned, r); }
; DI float siluf(float x) { return x * __builtin_amdgcn_rcpf(1.f + __expf(-x)); }
; DI void epi_store64(const float* Ct, int cb, const float* rn, int grp, const float* gain, bool silu, const float* bias,
;                     bf16_t* dst, size_t ldd, int dcol0, int m0, int Mmax) {
;     ...
;   for (int q = 0; q < 8; ++q) {
;     const int row = (tid >> 4) + 16 * q;
;     float4 v = *(const float4*)(Ct + row * 132 + cb + c);
;     v.x += bv.x; v.y += bv.y; v.z += bv.z; v.w += bv.w;
;     if (rn) { const float sc = rn[row * 2 + grp]; v.x *= sc * gv.x; v.y *= sc * gv.y; v.z *= sc * gv.z; v.w *= sc * gv.w; }
;     if (silu) { v.x = siluf(v.x); v.y = siluf(v.y); v.z = siluf(v.z); v.w = siluf(v.w); }
;     uint2 o; o.x = pack2(v.x, v.y); o.y = pack2(v.z, v.w);
;     *(uint2*)(dst + (size_t)(m0 + row) * ldd + dcol0 + c) = o;
;   }
; DI void inproj_tile(const Params& p, int l, int mt, int tn, char* smem) {
;     ...
;     epi_store64(Ct, 64, nullptr, 0, nullptr, true, nullptr, p.projZ, LDA_Z, c0 + 64, m0, T_TOK);
	v_pk_add_f32 v[6:7], v[6:7], 0 op_sel_hi:[1,0]
	s_nop 0
	v_mul_f32_e32 v5, 0xbfb8aa3b, v6
	v_exp_f32_e32 v5, v5
	v_pk_add_f32 v[8:9], v[8:9], 0 op_sel_hi:[1,0]
	v_add_f32_e32 v5, 1.0, v5
	v_rcp_f32_e32 v10, v5
	v_mul_f32_e32 v5, 0xbfb8aa3b, v7
	v_exp_f32_e32 v5, v5
	s_nop 0
	v_add_f32_e32 v5, 1.0, v5
	v_rcp_f32_e32 v11, v5
	v_mul_f32_e32 v5, 0xbfb8aa3b, v8
	v_exp_f32_e32 v5, v5
	v_pk_mul_f32 v[6:7], v[6:7], v[10:11]
	s_nop 0
	v_cvt_pk_bf16_f32 v6, v6, v7
	v_add_f32_e32 v5, 1.0, v5
	v_rcp_f32_e32 v10, v5
	v_mul_f32_e32 v5, 0xbfb8aa3b, v9
	v_exp_f32_e32 v5, v5
	s_nop 0
	v_add_f32_e32 v5, 1.0, v5
	v_rcp_f32_e32 v11, v5
	s_nop 0
	v_pk_mul_f32 v[8:9], v[8:9], v[10:11]
	s_nop 0
	v_cvt_pk_bf16_f32 v7, v8, v9
	v_add_u32_e32 v8, 64, v4
	v_ashrrev_i32_e32 v9, 31, v8
	v_lshlrev_b64 v[8:9], 11, v[8:9]
	v_lshl_add_u64 v[8:9], v[2:3], 0, v[8:9]
	global_store_dwordx2 v[8:9], v[6:7], off
	ds_read_b128 v[6:9], v0 offset:42496
	s_waitcnt lgkmcnt(0)
	v_pk_add_f32 v[6:7], v[6:7], 0 op_sel_hi:[1,0]
	s_nop 0
	v_mul_f32_e32 v5, 0xbfb8aa3b, v6
	v_exp_f32_e32 v5, v5
	v_pk_add_f32 v[8:9], v[8:9], 0 op_sel_hi:[1,0]
	v_add_f32_e32 v5, 1.0, v5
	v_rcp_f32_e32 v10, v5
	v_mul_f32_e32 v5, 0xbfb8aa3b, v7
	v_exp_f32_e32 v5, v5
	s_nop 0
	v_add_f32_e32 v5, 1.0, v5
	v_rcp_f32_e32 v11, v5
	v_mul_f32_e32 v5, 0xbfb8aa3b, v8
	v_exp_f32_e32 v5, v5
	v_pk_mul_f32 v[6:7], v[6:7], v[10:11]
	s_nop 0
	v_cvt_pk_bf16_f32 v6, v6, v7
	v_add_f32_e32 v5, 1.0, v5
	v_rcp_f32_e32 v10, v5
	v_mul_f32_e32 v5, 0xbfb8aa3b, v9
	v_exp_f32_e32 v5, v5
	s_nop 0
	v_add_f32_e32 v5, 1.0, v5
	v_rcp_f32_e32 v11, v5
	s_nop 0
	v_pk_mul_f32 v[8:9], v[8:9], v[10:11]
	s_nop 0
	v_cvt_pk_bf16_f32 v7, v8, v9
	v_add_u32_e32 v8, 0x50, v4
	v_ashrrev_i32_e32 v9, 31, v8
	v_lshlrev_b64 v[8:9], 11, v[8:9]
	v_lshl_add_u64 v[8:9], v[2:3], 0, v[8:9]
	global_store_dwordx2 v[8:9], v[6:7], off
	ds_read_b128 v[6:9], v0 offset:50944
	s_waitcnt lgkmcnt(0)
	v_pk_add_f32 v[6:7], v[6:7], 0 op_sel_hi:[1,0]
	s_nop 0
	v_mul_f32_e32 v5, 0xbfb8aa3b, v6
	v_exp_f32_e32 v5, v5
	v_pk_add_f32 v[8:9], v[8:9], 0 op_sel_hi:[1,0]
	v_add_f32_e32 v5, 1.0, v5
	v_rcp_f32_e32 v10, v5
	v_mul_f32_e32 v5, 0xbfb8aa3b, v7
	v_exp_f32_e32 v5, v5
	s_nop 0
	v_add_f32_e32 v5, 1.0, v5
	v_rcp_f32_e32 v11, v5
	v_mul_f32_e32 v5, 0xbfb8aa3b, v8
	v_exp_f32_e32 v5, v5
	v_pk_mul_f32 v[6:7], v[6:7], v[10:11]
	s_nop 0
	v_cvt_pk_bf16_f32 v6, v6, v7
	v_add_f32_e32 v5, 1.0, v5
	v_rcp_f32_e32 v10, v5
	v_mul_f32_e32 v5, 0xbfb8aa3b, v9
	v_exp_f32_e32 v5, v5
	s_nop 0
	v_add_f32_e32 v5, 1.0, v5
	v_rcp_f32_e32 v11, v5
	s_nop 0
	v_pk_mul_f32 v[8:9], v[8:9], v[10:11]
	s_nop 0
	v_cvt_pk_bf16_f32 v7, v8, v9
	v_add_u32_e32 v8, 0x60, v4
	v_ashrrev_i32_e32 v9, 31, v8
	v_lshlrev_b64 v[8:9], 11, v[8:9]
	v_lshl_add_u64 v[8:9], v[2:3], 0, v[8:9]
	global_store_dwordx2 v[8:9], v[6:7], off
	ds_read_b128 v[6:9], v0 offset:59392
	v_add_u32_e32 v4, 0x70, v4
	v_ashrrev_i32_e32 v5, 31, v4
	v_lshlrev_b64 v[4:5], 11, v[4:5]
	v_lshl_add_u64 v[2:3], v[2:3], 0, v[4:5]
	s_waitcnt lgkmcnt(0)
	v_pk_add_f32 v[6:7], v[6:7], 0 op_sel_hi:[1,0]
	v_pk_add_f32 v[8:9], v[8:9], 0 op_sel_hi:[1,0]
	v_mul_f32_e32 v0, 0xbfb8aa3b, v6
	v_exp_f32_e32 v0, v0
	s_nop 0
	v_add_f32_e32 v0, 1.0, v0
	v_rcp_f32_e32 v10, v0
	v_mul_f32_e32 v0, 0xbfb8aa3b, v7
	v_exp_f32_e32 v0, v0
	s_nop 0
	v_add_f32_e32 v0, 1.0, v0
	v_rcp_f32_e32 v11, v0
	v_mul_f32_e32 v0, 0xbfb8aa3b, v8
	v_exp_f32_e32 v0, v0
	v_pk_mul_f32 v[6:7], v[6:7], v[10:11]
	s_nop 0
	v_cvt_pk_bf16_f32 v6, v6, v7
	v_add_f32_e32 v0, 1.0, v0
	v_rcp_f32_e32 v10, v0
	v_mul_f32_e32 v0, 0xbfb8aa3b, v9
	v_exp_f32_e32 v0, v0
	s_nop 0
	v_add_f32_e32 v0, 1.0, v0
	v_rcp_f32_e32 v11, v0
	s_nop 0
	v_pk_mul_f32 v[8:9], v[8:9], v[10:11]
	s_nop 0
	v_cvt_pk_bf16_f32 v7, v8, v9
	global_store_dwordx2 v[2:3], v[6:7], off

; #define G_STORE(ST, S, unused) do { char* d_ = smem + (ST) * STAGE; \
;     *(uint4*)(d_ + alo[0]) = S##a0; *(uint4*)(d_ + alo[1]) = S##a1; *(uint4*)(d_ + alo[2]) = S##a2; *(uint4*)(d_ + alo[3]) = S##a3; \
;     *(uint4*)(d_ + blo[0]) = S##b0; *(uint4*)(d_ + blo[1]) = S##b1; \
;     if (NBCH == 4) { *(uint4*)(d_ + blo[NBCH - 2]) = S##b2; *(uint4*)(d_ + blo[NBCH - 1]) = S##b3; } } while (0)
; template <int NJ, class RowA>
; DI void gemm_main(f32x16 (&acc)[2][NJ], const bf16_t* __restrict__ A, RowA rowA, size_t kstrideA, int m0, int Mmax,
;                   const bf16_t* __restrict__ Bt, size_t ldb, int n0, int nk, char* smem) {
;     ...
;   __syncthreads();
;   G_LOAD(x0, 0, 0);
;   G_LOAD(x1, 0, 1);
;   G_STORE(0, x0, 0);
;   __syncthreads();
; #pragma unroll 1
;   for (int kt = 0; kt < nk; kt += 2) {
;     G_LOAD(x0, 0, (kt + 2 < nk ? kt + 2 : nk - 1));
;     G_COMPUTE(0);
;     G_STORE(1, x1, 0);
;     __syncthreads();
;     G_LOAD(x1, 0, (kt + 3 < nk ? kt + 3 : nk - 1));
;     G_COMPUTE(1);
;     G_STORE(0, x0, 0);
;     __syncthreads();
;   }
.LBB0_2149:
	ds_read_b128 v[166:169], v0
	ds_read_b128 v[170:173], v139 offset:18432
	ds_read_b128 v[174:177], v139 offset:23040
	ds_read_b128 v[178:181], v0 offset:4608
	s_add_i32 s1, s0, 4
	s_min_u32 s1, s1, 15
	s_lshl_b32 s14, s1, 7
	v_lshl_add_u64 v[98:99], v[122:123], 0, s[14:15]
	v_lshl_add_u64 v[102:103], v[124:125], 0, s[14:15]
	v_lshl_add_u64 v[106:107], v[126:127], 0, s[14:15]
	v_lshl_add_u64 v[110:111], v[128:129], 0, s[14:15]
	v_lshl_add_u64 v[114:115], v[130:131], 0, s[14:15]
	v_lshl_add_u64 v[118:119], v[132:133], 0, s[14:15]
	s_add_i32 s0, s0, 2
	v_lshl_add_u64 v[158:159], v[134:135], 0, s[14:15]
	v_lshl_add_u64 v[160:161], v[136:137], 0, s[14:15]
	s_setprio 1
	ds_read_b128 v[182:185], v0 offset:32
	ds_read_b128 v[186:189], v139 offset:18464
	ds_read_b128 v[190:193], v139 offset:23072
	ds_read_b128 v[194:197], v0 offset:4640
	s_waitcnt lgkmcnt(4)
	v_mfma_f32_32x32x16_bf16 v[50:65], v[166:169], v[170:173], v[50:65]
	global_load_dwordx4 v[98:101], v[98:99], off
	v_mfma_f32_32x32x16_bf16 v[34:49], v[166:169], v[174:177], v[34:49]
	global_load_dwordx4 v[102:105], v[102:103], off
	v_mfma_f32_32x32x16_bf16 v[18:33], v[178:181], v[170:173], v[18:33]
	global_load_dwordx4 v[106:109], v[106:107], off
	v_mfma_f32_32x32x16_bf16 v[2:17], v[178:181], v[174:177], v[2:17]
	global_load_dwordx4 v[110:113], v[110:111], off
	ds_read_b128 v[166:169], v0 offset:64
	ds_read_b128 v[170:173], v139 offset:18496
	ds_read_b128 v[174:177], v139 offset:23104
	ds_read_b128 v[178:181], v0 offset:4672
	s_waitcnt lgkmcnt(4)
	v_mfma_f32_32x32x16_bf16 v[50:65], v[182:185], v[186:189], v[50:65]
	global_load_dwordx4 v[114:117], v[114:115], off
	v_mfma_f32_32x32x16_bf16 v[34:49], v[182:185], v[190:193], v[34:49]
	global_load_dwordx4 v[118:121], v[118:119], off
	v_mfma_f32_32x32x16_bf16 v[18:33], v[194:197], v[186:189], v[18:33]
	global_load_dwordx4 v[146:149], v[160:161], off
	v_mfma_f32_32x32x16_bf16 v[2:17], v[194:197], v[190:193], v[2:17]
	global_load_dwordx4 v[150:153], v[158:159], off
	ds_read_b128 v[182:185], v0 offset:96
	ds_read_b128 v[186:189], v139 offset:18528
	ds_read_b128 v[190:193], v139 offset:23136
	ds_read_b128 v[194:197], v0 offset:4704
	s_waitcnt lgkmcnt(4)
	v_mfma_f32_32x32x16_bf16 v[50:65], v[166:169], v[170:173], v[50:65]
	s_waitcnt vmcnt(8)
	ds_write_b128 v138, v[74:77] offset:36864
	v_mfma_f32_32x32x16_bf16 v[34:49], v[166:169], v[174:177], v[34:49]
	ds_write_b128 v140, v[78:81] offset:36864
	v_mfma_f32_32x32x16_bf16 v[18:33], v[178:181], v[170:173], v[18:33]
	ds_write_b128 v142, v[82:85] offset:36864
	v_mfma_f32_32x32x16_bf16 v[2:17], v[178:181], v[174:177], v[2:17]
	ds_write_b128 v144, v[86:89] offset:36864
	s_waitcnt lgkmcnt(4)
	v_mfma_f32_32x32x16_bf16 v[50:65], v[182:185], v[186:189], v[50:65]
	ds_write_b128 v138, v[90:93] offset:55296
	v_mfma_f32_32x32x16_bf16 v[34:49], v[182:185], v[190:193], v[34:49]
	ds_write_b128 v140, v[94:97] offset:55296
	v_mfma_f32_32x32x16_bf16 v[18:33], v[194:197], v[186:189], v[18:33]
	ds_write_b128 v142, v[66:69] offset:55296
	v_mfma_f32_32x32x16_bf16 v[2:17], v[194:197], v[190:193], v[2:17]
	ds_write_b128 v144, v[70:73] offset:55296
	s_setprio 0
	s_min_u32 s1, s0, 12
	s_lshl_b32 s14, s1, 7
	v_lshl_add_u64 v[66:67], v[122:123], 0, s[14:15]
	v_lshl_add_u64 v[68:69], v[124:125], 0, s[14:15]
	v_lshl_add_u64 v[70:71], v[126:127], 0, s[14:15]
	v_lshl_add_u64 v[72:73], v[128:129], 0, s[14:15]
	v_lshl_add_u64 v[90:91], v[130:131], 0, s[14:15]
	v_lshl_add_u64 v[94:95], v[132:133], 0, s[14:15]
	s_waitcnt lgkmcnt(0)
	s_barrier
	ds_read_b128 v[166:169], v0 offset:36864
	ds_read_b128 v[170:173], v139 offset:55296
	ds_read_b128 v[174:177], v139 offset:59904
	ds_read_b128 v[178:181], v0 offset:41472
	v_lshl_add_u64 v[154:155], v[134:135], 0, s[14:15]
	v_lshl_add_u64 v[156:157], v[136:137], 0, s[14:15]
	s_setprio 1
	ds_read_b128 v[182:185], v0 offset:36896
	ds_read_b128 v[186:189], v139 offset:55328
	ds_read_b128 v[190:193], v139 offset:59936
	ds_read_b128 v[194:197], v0 offset:41504
	s_waitcnt lgkmcnt(4)
	v_mfma_f32_32x32x16_bf16 v[50:65], v[166:169], v[170:173], v[50:65]
	global_load_dwordx4 v[74:77], v[66:67], off offset:384
	v_mfma_f32_32x32x16_bf16 v[34:49], v[166:169], v[174:177], v[34:49]
	global_load_dwordx4 v[78:81], v[68:69], off offset:384
	v_mfma_f32_32x32x16_bf16 v[18:33], v[178:181], v[170:173], v[18:33]
	global_load_dwordx4 v[82:85], v[70:71], off offset:384
	v_mfma_f32_32x32x16_bf16 v[2:17], v[178:181], v[174:177], v[2:17]
	global_load_dwordx4 v[86:89], v[72:73], off offset:384
	ds_read_b128 v[166:169], v0 offset:36928
	ds_read_b128 v[170:173], v139 offset:55360
	ds_read_b128 v[174:177], v139 offset:59968
	ds_read_b128 v[178:181], v0 offset:41536
	s_waitcnt lgkmcnt(4)
	v_mfma_f32_32x32x16_bf16 v[50:65], v[182:185], v[186:189], v[50:65]
	global_load_dwordx4 v[90:93], v[90:91], off offset:384
	v_mfma_f32_32x32x16_bf16 v[34:49], v[182:185], v[190:193], v[34:49]
	global_load_dwordx4 v[94:97], v[94:95], off offset:384
	v_mfma_f32_32x32x16_bf16 v[18:33], v[194:197], v[186:189], v[18:33]
	global_load_dwordx4 v[66:69], v[154:155], off offset:384
	v_mfma_f32_32x32x16_bf16 v[2:17], v[194:197], v[190:193], v[2:17]
	global_load_dwordx4 v[70:73], v[156:157], off offset:384
	ds_read_b128 v[182:185], v0 offset:36960
	ds_read_b128 v[186:189], v139 offset:55392
	ds_read_b128 v[190:193], v139 offset:60000
	ds_read_b128 v[194:197], v0 offset:41568
	s_waitcnt lgkmcnt(4)
	v_mfma_f32_32x32x16_bf16 v[50:65], v[166:169], v[170:173], v[50:65]
	s_waitcnt vmcnt(8)
	ds_write_b128 v138, v[98:101]
	v_mfma_f32_32x32x16_bf16 v[34:49], v[166:169], v[174:177], v[34:49]
	ds_write_b128 v140, v[102:105]
	v_mfma_f32_32x32x16_bf16 v[18:33], v[178:181], v[170:173], v[18:33]
	ds_write_b128 v142, v[106:109]
	v_mfma_f32_32x32x16_bf16 v[2:17], v[178:181], v[174:177], v[2:17]
	ds_write_b128 v144, v[110:113]
	s_waitcnt lgkmcnt(4)
	v_mfma_f32_32x32x16_bf16 v[50:65], v[182:185], v[186:189], v[50:65]
	ds_write_b128 v138, v[114:117] offset:18432
	v_mfma_f32_32x32x16_bf16 v[34:49], v[182:185], v[190:193], v[34:49]
	ds_write_b128 v140, v[118:121] offset:18432
	v_mfma_f32_32x32x16_bf16 v[18:33], v[194:197], v[186:189], v[18:33]
	ds_write_b128 v142, v[150:153] offset:18432
	v_mfma_f32_32x32x16_bf16 v[2:17], v[194:197], v[190:193], v[2:17]
	ds_write_b128 v144, v[146:149] offset:18432
	s_setprio 0
	s_cmp_lt_u32 s0, 14
	s_waitcnt lgkmcnt(0)
	s_barrier
; #define TIDX (tid_launder())
; DI void epi_storeVF(const float* Ct, int cb, bf16_t* dst) {
;   for (int idx = TIDX; idx < 1024; idx += 256) {
;     const int kt4 = idx >> 8, slot = idx & 255, r = slot & 31, hh = (slot >> 5) & 1, s2 = (slot >> 6) & 1, dt = slot >> 7;
;     float v[8];
; DI void inproj_tile(const Params& p, int l, int mt, int tn, char* smem) {
;     ...
;   } else if (tn == 9) {
;     epi_storeKF(Ct, 0, nullptr, 0, nullptr, p.kidxF + ((size_t)b * 64 + s0 / 32) * 2048);
;     epi_store64(Ct, 64, nullptr, 0, nullptr, false, nullptr, p.projA, LDA_A, tn * 128 + 64, m0, T_TOK);
;   } else if (tn == 10) {
;     epi_rownorm(Ct, rn, 64);
;     epi_store64(Ct, 0, nullptr, 0, nullptr, false, nullptr, p.projA, LDA_A, 1280, m0, T_TOK);
;     epi_storeKF(Ct, 64, rn, 1, p.c_k_norm + (l * 3 + 1) * 64, p.kselF + ((size_t)b * 64 + s0 / 32) * 2048);
;   } else if (tn == 11) {
;     epi_rownorm(Ct, rn, 64);
;     epi_storeKF(Ct, 0, rn, 0, p.c_k_norm + (l * 3 + 2) * 64, p.kwinF + ((size_t)b * 64 + s0 / 32) * 2048);
;     epi_storeVF(Ct, 64, p.vselT + ((size_t)b * 64 + s0 / 32) * 2048);
;   } else if (tn == 12) {
;     epi_storeVF(Ct, 0, p.vwinT + ((size_t)b * 64 + s0 / 32) * 2048);
	s_cbranch_scc1 .LBB0_2149
	v_mov_b32_e32 v0, v230
	s_waitcnt vmcnt(1)
	v_mov_b32_e32 v66, v230
	v_and_b32_e32 v67, 31, v0
	v_lshrrev_b32_e32 v0, 3, v0
	v_and_b32_e32 v0, 4, v0
	v_lshrrev_b32_e32 v68, 1, v66
	v_and_or_b32 v0, v68, s47, v0
	v_and_or_b32 v66, v66, 64, v67
	v_mul_lo_u32 v0, v0, s79
	v_lshl_add_u32 v0, v66, 2, v0
	ds_write2_b32 v0, v50, v34 offset1:32
	ds_write2_b32 v0, v51, v35 offset0:132 offset1:164
	v_add_u32_e32 v34, 0x400, v0
	ds_write2_b32 v34, v52, v36 offset0:8 offset1:40
	ds_write2_b32 v34, v53, v37 offset0:140 offset1:172
	v_add_u32_e32 v34, 0x1000, v0
	ds_write2_b32 v34, v54, v38 offset0:32 offset1:64
	ds_write2_b32 v34, v55, v39 offset0:164 offset1:196
	v_add_u32_e32 v34, 0x1400, v0
	ds_write2_b32 v34, v56, v40 offset0:40 offset1:72
	ds_write2_b32 v34, v57, v41 offset0:172 offset1:204
	v_add_u32_e32 v34, 0x2000, v0
	ds_write2_b32 v34, v58, v42 offset0:64 offset1:96
	ds_write2_b32 v34, v59, v43 offset0:196 offset1:228
	v_add_u32_e32 v34, 0x2400, v0
	ds_write2_b32 v34, v60, v44 offset0:72 offset1:104
	ds_write2_b32 v34, v61, v45 offset0:204 offset1:236
	v_add_u32_e32 v34, 0x3000, v0
	ds_write2_b32 v34, v62, v46 offset0:96 offset1:128
	v_add_u32_e32 v34, 0x3200, v0
	ds_write2_b32 v34, v63, v47 offset0:100 offset1:132
	v_add_u32_e32 v34, 0x3400, v0
	ds_write2_b32 v34, v64, v48 offset0:104 offset1:136
	v_add_u32_e32 v34, 0x3600, v0
	ds_write2_b32 v34, v65, v49 offset0:108 offset1:140
	v_add_u32_e32 v34, 0x4000, v0
	ds_write2_b32 v34, v18, v2 offset0:128 offset1:160
	v_add_u32_e32 v2, 0x4400, v0
	ds_write2_b32 v2, v19, v3 offset0:4 offset1:36
	ds_write2_b32 v2, v20, v4 offset0:136 offset1:168
	v_add_u32_e32 v2, 0x4800, v0
	ds_write2_b32 v2, v21, v5 offset0:12 offset1:44
	v_add_u32_e32 v2, 0x5000, v0
	ds_write2_b32 v2, v22, v6 offset0:160 offset1:192
	v_add_u32_e32 v2, 0x5400, v0
	ds_write2_b32 v2, v23, v7 offset0:36 offset1:68
	ds_write2_b32 v2, v24, v8 offset0:168 offset1:200
	v_add_u32_e32 v2, 0x5800, v0
	ds_write2_b32 v2, v25, v9 offset0:44 offset1:76
	v_add_u32_e32 v2, 0x6000, v0
	ds_write2_b32 v2, v26, v10 offset0:192 offset1:224
	v_add_u32_e32 v2, 0x6400, v0
	ds_write2_b32 v2, v27, v11 offset0:68 offset1:100
	ds_write2_b32 v2, v28, v12 offset0:200 offset1:232
	v_add_u32_e32 v2, 0x6800, v0
	ds_write2_b32 v2, v29, v13 offset0:76 offset1:108
	v_add_u32_e32 v2, 0x7200, v0
	ds_write2_b32 v2, v30, v14 offset0:96 offset1:128
	v_add_u32_e32 v2, 0x7400, v0
	ds_write2_b32 v2, v31, v15 offset0:100 offset1:132
	v_add_u32_e32 v2, 0x7600, v0
	v_add_u32_e32 v0, 0x7800, v0
	s_cmp_gt_u32 s35, 3
	s_mov_b64 s[0:1], -1
	ds_write2_b32 v2, v32, v16 offset0:104 offset1:136
	ds_write2_b32 v0, v33, v17 offset0:108 offset1:140
	s_waitcnt lgkmcnt(0)
	s_barrier
	s_cbranch_scc0 .LBB0_2277
	s_cmp_lg_u32 s35, 4
	s_cbranch_scc0 .LBB0_2236
	s_cmp_gt_u32 s35, 8
	s_cbranch_scc0 .LBB0_2233
	s_ashr_i32 s0, s2, 6
	s_add_i32 s2, s0, s3
	s_ashr_i32 s0, s13, 31
	s_lshr_b32 s0, s0, 21
	s_add_i32 s0, s13, s0
	s_and_b32 s0, s0, 0xfffff800
	s_sub_i32 s14, s13, s0
	s_mov_b64 s[0:1], -1
	s_mov_b64 s[6:7], 0
	s_cmp_lt_i32 s68, -1
	s_mov_b64 s[4:5], 0
	s_cbranch_scc1 .LBB0_2199
	s_cmp_gt_i32 s68, -1
	s_cbranch_scc0 .LBB0_2169
	s_cmp_eq_u32 s68, 0
	s_mov_b64 s[4:5], -1
	s_cbranch_scc0 .LBB0_2168
	v_mov_b32_e32 v2, v230
	s_movk_i32 s0, 0x400
	s_nop 0
	v_cmp_gt_i32_e32 vcc, s0, v2
	s_and_saveexec_b64 s[0:1], vcc
	s_movk_i32 s36, 0x2ff
	s_cbranch_execz .LBB0_2159
	s_ashr_i32 s3, s2, 31
	s_ashr_i32 s4, s14, 5
	v_readlane_b32 s16, v250, 34
	s_ashr_i32 s5, s4, 31
	s_lshl_b64 s[8:9], s[2:3], 18
	v_readlane_b32 s22, v250, 40
	v_readlane_b32 s23, v250, 41
	s_add_u32 s3, s22, s8
	s_addc_u32 s8, s23, s9
	s_lshl_b64 s[4:5], s[4:5], 12
	s_add_u32 s4, s3, s4
	v_and_b32_e32 v0, 31, v2
	s_addc_u32 s5, s8, s5
	v_lshlrev_b32_e32 v3, 2, v0
	v_lshlrev_b32_e32 v4, 3, v2
	s_mov_b64 s[8:9], 0
	v_readlane_b32 s17, v250, 35
	v_readlane_b32 s18, v250, 36
	v_readlane_b32 s19, v250, 37
	v_readlane_b32 s20, v250, 38
	v_readlane_b32 s21, v250, 39
	v_readlane_b32 s24, v250, 42
	v_readlane_b32 s25, v250, 43
	v_readlane_b32 s26, v250, 44
	v_readlane_b32 s27, v250, 45
	v_readlane_b32 s28, v250, 46
	v_readlane_b32 s29, v250, 47
	v_readlane_b32 s30, v250, 48
	v_readlane_b32 s31, v250, 49
